# full stack + non-temporal hint on the contiguous unorm8 gate-byte stores (proj main + HALFN epilogues): keeps weights/activations resident in L2/MALL
# speedup vs baseline: 1.0052x; 1.0052x over previous
; __device__ __forceinline__ float sigmoid_f(float x) { return __builtin_amdgcn_rcpf(1.0f + __builtin_amdgcn_exp2f(-1.4426950409f * x)); }
;     __device__ __forceinline__ void body_gate(f32x4 (&acc)[2][2][4][2], const Unit& u, int wr, int wc, int fr, int fq, int gbase, const float (&rsv)[2][4]) const {
;         EPI_ROWS_BEGIN
;             const float rs = rsv[ai][m];
; #pragma unroll
;             for (int bj = 0; bj < 2; ++bj) { if (u.half != 0 && bj == 1) continue;
;                 const int gcol = gbase + (bj + (u.half == 2 ? 1 : 0)) * 128 + wc * 32 + 8 * fq;
;                 f32x4 v0 = acc[ai][bj][m][0] * rs, v1 = acc[ai][bj][m][1] * rs;
; #pragma unroll
;                 for (int j = 0; j < 4; ++j) { v0[j] = sigmoid_f(v0[j]); v1[j] = sigmoid_f(v1[j]); }
;                 u32x2 w; w.x = pk_unorm8(v0); w.y = pk_unorm8(v1);
;                 *(u32x2*)((unsigned char*)P + (size_t)row * ROWB + GATE_B0 + gcol) = w;
;             }
;         EPI_END
;     }
;     __device__ __forceinline__ void operator()(f32x4 (&acc)[2][2][4][2], const Unit& u, int wr, int wc, int fr, int fq) const {
;     ...
;         const int pn = u.pn + pn0;
;         if (pn < 8) body_pair<0>(acc, u, wr, wc, fr, fq, OQ + pn * 128, rsv);
;         else if (pn < 16) body_pair<1>(acc, u, wr, wc, fr, fq, OAB + (pn - 8) * 128, rsv);
;         else if (pn < 20) body<0>(acc, u, wr, wc, fr, fq, OBIN + (pn - 16) * 256, rsv);
;         else if (pn < 24) body<1>(acc, u, wr, wc, fr, fq, OBZ + (pn - 20) * 256, rsv);
;         else if (pn < 32) body_pair<2>(acc, u, wr, wc, fr, fq, OV + (pn - 24) * 128, rsv);
;         else if (pn < 36) body<1>(acc, u, wr, wc, fr, fq, OCZ + (pn - 32) * 256, rsv);
;         else body_gate(acc, u, wr, wc, fr, fq, (pn - 36) * 256, rsv);
.LBB0_200:
	s_cmp_gt_u32 s52, 15
	s_cbranch_scc0 .LBB0_218
	s_cmp_gt_u32 s52, 19
	s_cbranch_scc0 .LBB0_215
	s_cmp_gt_u32 s52, 23
	s_cbranch_scc0 .LBB0_212
	s_cmp_gt_u32 s52, 31
	s_cbranch_scc0 .LBB0_209
	v_mov_b32_e32 v159, v158
	v_pk_mul_f32 v[178:179], v[126:127], v[158:159] op_sel_hi:[1,0]
	s_lshl_b32 s6, s52, 8
	v_mul_f32_e32 v160, 0xbfb8aa3b, v178
	v_exp_f32_e32 v170, v160
	v_mad_i64_i32 v[168:169], s[4:5], v154, s33, 0
	v_pk_mul_f32 v[174:175], v[128:129], v[158:159] op_sel_hi:[1,0]
	v_add_f32_e32 v170, 1.0, v170
	v_rcp_f32_e32 v180, v170
	v_pk_mul_f32 v[160:161], v[124:125], v[158:159] op_sel_hi:[1,0]
	v_pk_mul_f32 v[176:177], v[122:123], v[158:159] op_sel_hi:[1,0]
	s_cmp_gt_u32 s52, 35
	v_lshlrev_b32_e32 v216, 3, v210
	s_mov_b64 s[4:5], -1
	v_lshl_add_u64 v[172:173], s[68:69], 0, v[168:169]
	v_mul_f32_e32 v218, 0xbfb8aa3b, v176
	v_mul_f32_e32 v217, 0xbfb8aa3b, v179
	v_mul_f32_e32 v215, 0xbfb8aa3b, v177
	v_mul_f32_e32 v214, 0xbfb8aa3b, v174
	v_mul_f32_e32 v213, 0xbfb8aa3b, v160
	v_mul_f32_e32 v212, 0xbfb8aa3b, v175
	v_mul_f32_e32 v211, 0xbfb8aa3b, v161
	v_pk_mul_f32 v[170:171], v[118:119], v[158:159]
	v_pk_mul_f32 v[168:169], v[110:111], v[158:159]
	s_cbranch_scc0 .LBB0_206
	v_exp_f32_e32 v159, v218
	v_exp_f32_e32 v183, v217
	v_exp_f32_e32 v219, v211
	s_mov_b32 s8, 0x437f0000
	v_add_f32_e32 v159, 1.0, v159
	v_rcp_f32_e32 v181, v159
	v_exp_f32_e32 v159, v215
	v_add_f32_e32 v183, 1.0, v183
	v_rcp_f32_e32 v184, v183
	v_exp_f32_e32 v183, v214
	v_add_f32_e32 v159, 1.0, v159
	v_rcp_f32_e32 v185, v159
	v_exp_f32_e32 v159, v213
	v_add_f32_e32 v183, 1.0, v183
	v_rcp_f32_e32 v186, v183
	v_exp_f32_e32 v183, v212
	v_add_f32_e32 v159, 1.0, v159
	v_rcp_f32_e32 v187, v159
	v_pk_fma_f32 v[184:185], v[184:185], s[8:9], 0.5 op_sel_hi:[1,0,0]
	v_add_f32_e32 v159, 1.0, v183
	v_rcp_f32_e32 v220, v159
	v_add_f32_e32 v159, 1.0, v219
	v_rcp_f32_e32 v221, v159
	v_pk_fma_f32 v[222:223], v[180:181], s[8:9], 0.5 op_sel_hi:[1,0,0]
	v_cvt_u32_f32_e32 v183, v184
	v_cvt_u32_f32_e32 v181, v222
	v_cvt_u32_f32_e32 v219, v185
	v_pk_fma_f32 v[184:185], v[186:187], s[8:9], 0.5 op_sel_hi:[1,0,0]
	v_lshlrev_b32_e32 v183, 8, v183
	v_cvt_u32_f32_sdwa v186, v184 dst_sel:WORD_1 dst_unused:UNUSED_PAD src0_sel:DWORD
	v_cvt_u32_f32_sdwa v187, v185 dst_sel:WORD_1 dst_unused:UNUSED_PAD src0_sel:DWORD
	v_pk_fma_f32 v[184:185], v[220:221], s[8:9], 0.5 op_sel_hi:[1,0,0]
	v_cvt_u32_f32_e32 v159, v223
	v_cvt_u32_f32_sdwa v184, v184 dst_sel:BYTE_3 dst_unused:UNUSED_PAD src0_sel:DWORD
	v_or_b32_e32 v181, v183, v181
	v_or_b32_e32 v181, v181, v186
	v_cvt_u32_f32_sdwa v185, v185 dst_sel:BYTE_3 dst_unused:UNUSED_PAD src0_sel:DWORD
	v_or_b32_e32 v184, v181, v184
	v_mul_f32_e32 v181, 0xbfb8aa3b, v170
	s_add_i32 s4, s27, s6
	s_lshr_b32 s98, s4, 7
	s_and_b32 s98, s98, 14
	s_bfe_u32 s99, s4, 0x10006
	s_or_b32 s98, s98, s99
	v_sub_u32_e32 v230, s98, v1
	s_lshr_b32 s98, s4, 11
	s_lshl_b32 s98, s98, 11
	s_and_b32 s99, s4, 32
	s_lshl_b32 s99, s99, 4
	s_add_i32 s98, s98, s99
	v_lshlrev_b32_e32 v219, 8, v219
	v_exp_f32_e32 v181, v181
	v_lshl_add_u32 v182, v143, 7, s98
	v_lshl_add_u32 v182, v1, 3, v182
	v_mad_i32_i24 v182, v230, s33, v182
	v_or_b32_e32 v159, v219, v159
	v_or_b32_e32 v159, v159, v187
	v_lshl_add_u64 v[186:187], v[172:173], 0, s[64:65]
	v_ashrrev_i32_e32 v183, 31, v182
	v_or_b32_e32 v185, v159, v185
	v_lshl_add_u64 v[220:221], v[186:187], 0, v[182:183]
	v_mov_b32_e32 v159, v158
	v_mul_f32_e32 v219, 0xbfb8aa3b, v168
	global_store_dwordx2 v[220:221], v[184:185], off nt
	v_pk_mul_f32 v[184:185], v[120:121], v[158:159]
	v_exp_f32_e32 v219, v219
	v_pk_mul_f32 v[220:221], v[112:113], v[158:159]
	v_add_f32_e32 v159, 1.0, v181
	v_mul_f32_e32 v181, 0xbfb8aa3b, v171
	v_exp_f32_e32 v181, v181
	v_rcp_f32_e32 v222, v159
	v_add_f32_e32 v159, 1.0, v219
	v_mul_f32_e32 v219, 0xbfb8aa3b, v169
	v_exp_f32_e32 v219, v219
	v_rcp_f32_e32 v223, v159
	v_add_f32_e32 v159, 1.0, v181
	v_mul_f32_e32 v181, 0xbfb8aa3b, v184
	v_exp_f32_e32 v181, v181
	v_mul_f32_e32 v184, 0xbfb8aa3b, v220
	v_exp_f32_e32 v184, v184
	v_rcp_f32_e32 v224, v159
	v_add_f32_e32 v159, 1.0, v219
	v_rcp_f32_e32 v225, v159
	v_add_f32_e32 v159, 1.0, v181
	v_mul_f32_e32 v181, 0xbfb8aa3b, v185
	v_rcp_f32_e32 v220, v159
	v_add_f32_e32 v159, 1.0, v184
	v_exp_f32_e32 v181, v181
	v_mul_f32_e32 v184, 0xbfb8aa3b, v221
	v_exp_f32_e32 v184, v184
	v_rcp_f32_e32 v221, v159
	v_add_f32_e32 v159, 1.0, v181
	v_rcp_f32_e32 v226, v159
	v_add_f32_e32 v159, 1.0, v184
	v_rcp_f32_e32 v227, v159
	v_pk_fma_f32 v[222:223], v[222:223], s[8:9], 0.5 op_sel_hi:[1,0,0]
	v_pk_fma_f32 v[220:221], v[220:221], s[8:9], 0.5 op_sel_hi:[1,0,0]
	v_cvt_u32_f32_e32 v159, v223
	v_cvt_u32_f32_e32 v181, v222
	v_pk_fma_f32 v[222:223], v[224:225], s[8:9], 0.5 op_sel_hi:[1,0,0]
	v_add_u32_e32 v184, 0x400, v182
	v_cvt_u32_f32_e32 v185, v222
	v_cvt_u32_f32_e32 v219, v223
	v_cvt_u32_f32_sdwa v222, v220 dst_sel:WORD_1 dst_unused:UNUSED_PAD src0_sel:DWORD
	v_cvt_u32_f32_sdwa v223, v221 dst_sel:WORD_1 dst_unused:UNUSED_PAD src0_sel:DWORD
	v_pk_fma_f32 v[220:221], v[226:227], s[8:9], 0.5 op_sel_hi:[1,0,0]
	v_lshlrev_b32_e32 v219, 8, v219
	v_cvt_u32_f32_sdwa v220, v220 dst_sel:BYTE_3 dst_unused:UNUSED_PAD src0_sel:DWORD
	v_cvt_u32_f32_sdwa v221, v221 dst_sel:BYTE_3 dst_unused:UNUSED_PAD src0_sel:DWORD
	v_lshlrev_b32_e32 v185, 8, v185
	v_or_b32_e32 v159, v219, v159
	v_or_b32_e32 v181, v185, v181
	v_or_b32_e32 v159, v159, v223
	v_or_b32_e32 v181, v181, v222
	v_ashrrev_i32_e32 v185, 31, v184
	v_or_b32_e32 v221, v159, v221
	v_or_b32_e32 v220, v181, v220
	v_lshl_add_u64 v[186:187], v[186:187], 0, v[184:185]
	global_store_dwordx2 v[186:187], v[220:221], off nt
	v_pk_mul_f32 v[220:221], v[114:115], v[156:157] op_sel_hi:[1,0]
; __device__ __forceinline__ float sigmoid_f(float x) { return __builtin_amdgcn_rcpf(1.0f + __builtin_amdgcn_exp2f(-1.4426950409f * x)); }
;     __device__ __forceinline__ void body_gate(f32x4 (&acc)[2][2][4][2], const Unit& u, int wr, int wc, int fr, int fq, int gbase, const float (&rsv)[2][4]) const {
;         EPI_ROWS_BEGIN
;             const float rs = rsv[ai][m];
; #pragma unroll
;             for (int bj = 0; bj < 2; ++bj) { if (u.half != 0 && bj == 1) continue;
;                 const int gcol = gbase + (bj + (u.half == 2 ? 1 : 0)) * 128 + wc * 32 + 8 * fq;
;                 f32x4 v0 = acc[ai][bj][m][0] * rs, v1 = acc[ai][bj][m][1] * rs;
; #pragma unroll
;                 for (int j = 0; j < 4; ++j) { v0[j] = sigmoid_f(v0[j]); v1[j] = sigmoid_f(v1[j]); }
;                 u32x2 w; w.x = pk_unorm8(v0); w.y = pk_unorm8(v1);
;                 *(u32x2*)((unsigned char*)P + (size_t)row * ROWB + GATE_B0 + gcol) = w;
;             }
;         EPI_END
;     }
	v_pk_mul_f32 v[222:223], v[106:107], v[156:157] op_sel_hi:[1,0]
	v_mul_f32_e32 v159, 0xbfb8aa3b, v220
	v_exp_f32_e32 v159, v159
	v_mul_f32_e32 v181, 0xbfb8aa3b, v222
	v_exp_f32_e32 v181, v181
	v_mul_f32_e32 v219, 0xbfb8aa3b, v223
	v_add_f32_e32 v159, 1.0, v159
	v_rcp_f32_e32 v220, v159
	v_add_f32_e32 v159, 1.0, v181
	v_mul_f32_e32 v181, 0xbfb8aa3b, v221
	v_exp_f32_e32 v181, v181
	v_pk_mul_f32 v[186:187], v[116:117], v[156:157] op_sel_hi:[1,0]
	v_exp_f32_e32 v219, v219
	v_rcp_f32_e32 v221, v159
	v_add_f32_e32 v159, 1.0, v181
	v_mul_f32_e32 v181, 0xbfb8aa3b, v186
	v_pk_mul_f32 v[224:225], v[108:109], v[156:157] op_sel_hi:[1,0]
	v_exp_f32_e32 v181, v181
	v_mul_f32_e32 v186, 0xbfb8aa3b, v224
	v_rcp_f32_e32 v222, v159
	v_add_f32_e32 v159, 1.0, v219
	v_exp_f32_e32 v219, v186
	v_rcp_f32_e32 v223, v159
	v_add_f32_e32 v159, 1.0, v181
	v_mul_f32_e32 v181, 0xbfb8aa3b, v187
	v_exp_f32_e32 v181, v181
	v_mul_f32_e32 v187, 0xbfb8aa3b, v225
	v_rcp_f32_e32 v186, v159
	v_add_f32_e32 v159, 1.0, v219
	v_exp_f32_e32 v219, v187
	v_rcp_f32_e32 v187, v159
	v_add_f32_e32 v159, 1.0, v181
	v_rcp_f32_e32 v224, v159
	v_add_f32_e32 v159, 1.0, v219
	v_rcp_f32_e32 v225, v159
	v_pk_fma_f32 v[220:221], v[220:221], s[8:9], 0.5 op_sel_hi:[1,0,0]
	v_pk_fma_f32 v[186:187], v[186:187], s[8:9], 0.5 op_sel_hi:[1,0,0]
	v_cvt_u32_f32_e32 v159, v221
	v_cvt_u32_f32_e32 v181, v220
	v_pk_fma_f32 v[220:221], v[222:223], s[8:9], 0.5 op_sel_hi:[1,0,0]
	v_cvt_u32_f32_sdwa v222, v187 dst_sel:WORD_1 dst_unused:UNUSED_PAD src0_sel:DWORD
	v_cvt_u32_f32_e32 v219, v220
	v_cvt_u32_f32_e32 v220, v221
	v_cvt_u32_f32_sdwa v221, v186 dst_sel:WORD_1 dst_unused:UNUSED_PAD src0_sel:DWORD
	v_pk_fma_f32 v[186:187], v[224:225], s[8:9], 0.5 op_sel_hi:[1,0,0]
	v_lshlrev_b32_e32 v219, 8, v219
	v_cvt_u32_f32_sdwa v186, v186 dst_sel:BYTE_3 dst_unused:UNUSED_PAD src0_sel:DWORD
	v_cvt_u32_f32_sdwa v187, v187 dst_sel:BYTE_3 dst_unused:UNUSED_PAD src0_sel:DWORD
	v_lshlrev_b32_e32 v220, 8, v220
	v_or_b32_e32 v159, v220, v159
	v_or_b32_e32 v181, v219, v181
	v_or_b32_e32 v159, v159, v222
	v_or_b32_e32 v181, v181, v221
	v_or_b32_e32 v221, v159, v187
	v_or_b32_e32 v220, v181, v186
	v_mov_b64_e32 v[186:187], s[68:69]
	v_mad_i64_i32 v[222:223], s[4:5], v209, s33, v[186:187]
	v_lshl_add_u64 v[222:223], v[222:223], 0, s[64:65]
	v_lshl_add_u64 v[224:225], v[222:223], 0, v[182:183]
	global_store_dwordx2 v[224:225], v[220:221], off nt
	v_pk_mul_f32 v[224:225], v[98:99], v[156:157] op_sel_hi:[1,0]
	v_pk_mul_f32 v[226:227], v[90:91], v[156:157] op_sel_hi:[1,0]
	v_mul_f32_e32 v159, 0xbfb8aa3b, v224
	v_exp_f32_e32 v159, v159
	v_mul_f32_e32 v181, 0xbfb8aa3b, v226
	v_exp_f32_e32 v181, v181
	v_mul_f32_e32 v219, 0xbfb8aa3b, v227
	v_add_f32_e32 v159, 1.0, v159
	v_rcp_f32_e32 v224, v159
	v_add_f32_e32 v159, 1.0, v181
	v_mul_f32_e32 v181, 0xbfb8aa3b, v225
	v_exp_f32_e32 v181, v181
	v_exp_f32_e32 v219, v219
	v_pk_mul_f32 v[220:221], v[100:101], v[156:157] op_sel_hi:[1,0]
	v_pk_mul_f32 v[228:229], v[92:93], v[156:157] op_sel_hi:[1,0]
	v_rcp_f32_e32 v225, v159
	v_add_f32_e32 v159, 1.0, v181
	v_mul_f32_e32 v181, 0xbfb8aa3b, v220
	v_rcp_f32_e32 v226, v159
	v_add_f32_e32 v159, 1.0, v219
	v_exp_f32_e32 v181, v181
	v_mul_f32_e32 v219, 0xbfb8aa3b, v228
	v_exp_f32_e32 v219, v219
	v_rcp_f32_e32 v227, v159
	v_add_f32_e32 v159, 1.0, v181
	v_mul_f32_e32 v181, 0xbfb8aa3b, v221
	v_rcp_f32_e32 v220, v159
	v_add_f32_e32 v159, 1.0, v219
	v_exp_f32_e32 v181, v181
	v_mul_f32_e32 v219, 0xbfb8aa3b, v229
	v_exp_f32_e32 v219, v219
	v_rcp_f32_e32 v221, v159
	v_add_f32_e32 v159, 1.0, v181
	v_rcp_f32_e32 v228, v159
	v_add_f32_e32 v159, 1.0, v219
	v_rcp_f32_e32 v229, v159
	v_pk_fma_f32 v[224:225], v[224:225], s[8:9], 0.5 op_sel_hi:[1,0,0]
	v_pk_fma_f32 v[220:221], v[220:221], s[8:9], 0.5 op_sel_hi:[1,0,0]
	v_cvt_u32_f32_e32 v159, v225
	v_cvt_u32_f32_e32 v181, v224
	v_pk_fma_f32 v[224:225], v[226:227], s[8:9], 0.5 op_sel_hi:[1,0,0]
	v_cvt_u32_f32_sdwa v226, v221 dst_sel:WORD_1 dst_unused:UNUSED_PAD src0_sel:DWORD
	v_cvt_u32_f32_e32 v219, v224
	v_cvt_u32_f32_e32 v224, v225
	v_cvt_u32_f32_sdwa v225, v220 dst_sel:WORD_1 dst_unused:UNUSED_PAD src0_sel:DWORD
	v_pk_fma_f32 v[220:221], v[228:229], s[8:9], 0.5 op_sel_hi:[1,0,0]
	v_lshlrev_b32_e32 v219, 8, v219
	v_cvt_u32_f32_sdwa v220, v220 dst_sel:BYTE_3 dst_unused:UNUSED_PAD src0_sel:DWORD
	v_cvt_u32_f32_sdwa v221, v221 dst_sel:BYTE_3 dst_unused:UNUSED_PAD src0_sel:DWORD
	v_lshlrev_b32_e32 v224, 8, v224
	v_or_b32_e32 v159, v224, v159
	v_or_b32_e32 v181, v219, v181
	v_or_b32_e32 v159, v159, v226
	v_or_b32_e32 v181, v181, v225
	v_or_b32_e32 v221, v159, v221
	v_or_b32_e32 v220, v181, v220
	v_lshl_add_u64 v[222:223], v[222:223], 0, v[184:185]
	global_store_dwordx2 v[222:223], v[220:221], off nt
	v_pk_mul_f32 v[222:223], v[102:103], v[152:153] op_sel_hi:[1,0]
	v_pk_mul_f32 v[224:225], v[94:95], v[152:153] op_sel_hi:[1,0]
	v_mul_f32_e32 v159, 0xbfb8aa3b, v222
	v_exp_f32_e32 v159, v159
	v_mul_f32_e32 v181, 0xbfb8aa3b, v224
	v_exp_f32_e32 v181, v181
	v_mul_f32_e32 v219, 0xbfb8aa3b, v225
	v_add_f32_e32 v159, 1.0, v159
	v_rcp_f32_e32 v222, v159
	v_add_f32_e32 v159, 1.0, v181
	v_mul_f32_e32 v181, 0xbfb8aa3b, v223
	v_exp_f32_e32 v181, v181
	v_exp_f32_e32 v219, v219
	v_pk_mul_f32 v[220:221], v[104:105], v[152:153] op_sel_hi:[1,0]
	v_pk_mul_f32 v[226:227], v[96:97], v[152:153] op_sel_hi:[1,0]
	v_rcp_f32_e32 v223, v159
	v_add_f32_e32 v159, 1.0, v181
	v_mul_f32_e32 v181, 0xbfb8aa3b, v220
	v_rcp_f32_e32 v224, v159
	v_add_f32_e32 v159, 1.0, v219
	v_exp_f32_e32 v181, v181
	v_mul_f32_e32 v219, 0xbfb8aa3b, v226
	v_exp_f32_e32 v219, v219
	v_rcp_f32_e32 v225, v159
	v_add_f32_e32 v159, 1.0, v181
	v_mul_f32_e32 v181, 0xbfb8aa3b, v221
; __device__ __forceinline__ float sigmoid_f(float x) { return __builtin_amdgcn_rcpf(1.0f + __builtin_amdgcn_exp2f(-1.4426950409f * x)); }
;     __device__ __forceinline__ void body_gate(f32x4 (&acc)[2][2][4][2], const Unit& u, int wr, int wc, int fr, int fq, int gbase, const float (&rsv)[2][4]) const {
;         EPI_ROWS_BEGIN
;             const float rs = rsv[ai][m];
; #pragma unroll
;             for (int bj = 0; bj < 2; ++bj) { if (u.half != 0 && bj == 1) continue;
;                 const int gcol = gbase + (bj + (u.half == 2 ? 1 : 0)) * 128 + wc * 32 + 8 * fq;
;                 f32x4 v0 = acc[ai][bj][m][0] * rs, v1 = acc[ai][bj][m][1] * rs;
; #pragma unroll
;                 for (int j = 0; j < 4; ++j) { v0[j] = sigmoid_f(v0[j]); v1[j] = sigmoid_f(v1[j]); }
;                 u32x2 w; w.x = pk_unorm8(v0); w.y = pk_unorm8(v1);
;                 *(u32x2*)((unsigned char*)P + (size_t)row * ROWB + GATE_B0 + gcol) = w;
;             }
;         EPI_END
;     }
	v_rcp_f32_e32 v220, v159
	v_add_f32_e32 v159, 1.0, v219
	v_exp_f32_e32 v181, v181
	v_mul_f32_e32 v219, 0xbfb8aa3b, v227
	v_exp_f32_e32 v219, v219
	v_rcp_f32_e32 v221, v159
	v_add_f32_e32 v159, 1.0, v181
	v_rcp_f32_e32 v226, v159
	v_add_f32_e32 v159, 1.0, v219
	v_pk_fma_f32 v[222:223], v[222:223], s[8:9], 0.5 op_sel_hi:[1,0,0]
	v_rcp_f32_e32 v227, v159
	v_cvt_u32_f32_e32 v159, v223
	v_cvt_u32_f32_e32 v181, v222
	v_pk_fma_f32 v[222:223], v[224:225], s[8:9], 0.5 op_sel_hi:[1,0,0]
	v_pk_fma_f32 v[220:221], v[220:221], s[8:9], 0.5 op_sel_hi:[1,0,0]
	v_cvt_u32_f32_e32 v219, v222
	v_cvt_u32_f32_e32 v222, v223
	v_cvt_u32_f32_sdwa v223, v220 dst_sel:WORD_1 dst_unused:UNUSED_PAD src0_sel:DWORD
	v_cvt_u32_f32_sdwa v224, v221 dst_sel:WORD_1 dst_unused:UNUSED_PAD src0_sel:DWORD
	v_pk_fma_f32 v[220:221], v[226:227], s[8:9], 0.5 op_sel_hi:[1,0,0]
	v_lshlrev_b32_e32 v219, 8, v219
	v_cvt_u32_f32_sdwa v220, v220 dst_sel:BYTE_3 dst_unused:UNUSED_PAD src0_sel:DWORD
	v_cvt_u32_f32_sdwa v221, v221 dst_sel:BYTE_3 dst_unused:UNUSED_PAD src0_sel:DWORD
	v_lshlrev_b32_e32 v222, 8, v222
	v_or_b32_e32 v181, v219, v181
	v_or_b32_e32 v159, v222, v159
	v_or_b32_e32 v181, v181, v223
	v_mad_i64_i32 v[222:223], s[4:5], v208, s33, v[186:187]
	v_or_b32_e32 v159, v159, v224
	v_lshl_add_u64 v[222:223], v[222:223], 0, s[64:65]
	v_or_b32_e32 v221, v159, v221
	v_or_b32_e32 v220, v181, v220
	v_lshl_add_u64 v[224:225], v[222:223], 0, v[182:183]
	global_store_dwordx2 v[224:225], v[220:221], off nt
	v_pk_mul_f32 v[224:225], v[82:83], v[152:153] op_sel_hi:[1,0]
	v_pk_mul_f32 v[226:227], v[74:75], v[152:153] op_sel_hi:[1,0]
	v_mul_f32_e32 v159, 0xbfb8aa3b, v224
	v_exp_f32_e32 v159, v159
	v_mul_f32_e32 v181, 0xbfb8aa3b, v226
	v_exp_f32_e32 v181, v181
	v_mul_f32_e32 v219, 0xbfb8aa3b, v227
	v_add_f32_e32 v159, 1.0, v159
	v_rcp_f32_e32 v224, v159
	v_add_f32_e32 v159, 1.0, v181
	v_mul_f32_e32 v181, 0xbfb8aa3b, v225
	v_exp_f32_e32 v181, v181
	v_exp_f32_e32 v219, v219
	v_pk_mul_f32 v[220:221], v[84:85], v[152:153] op_sel_hi:[1,0]
	v_pk_mul_f32 v[228:229], v[76:77], v[152:153] op_sel_hi:[1,0]
	v_rcp_f32_e32 v225, v159
	v_add_f32_e32 v159, 1.0, v181
	v_mul_f32_e32 v181, 0xbfb8aa3b, v220
	v_rcp_f32_e32 v226, v159
	v_add_f32_e32 v159, 1.0, v219
	v_exp_f32_e32 v181, v181
	v_mul_f32_e32 v219, 0xbfb8aa3b, v228
	v_exp_f32_e32 v219, v219
	v_rcp_f32_e32 v227, v159
	v_add_f32_e32 v159, 1.0, v181
	v_mul_f32_e32 v181, 0xbfb8aa3b, v221
	v_rcp_f32_e32 v220, v159
	v_add_f32_e32 v159, 1.0, v219
	v_exp_f32_e32 v181, v181
	v_mul_f32_e32 v219, 0xbfb8aa3b, v229
	v_exp_f32_e32 v219, v219
	v_rcp_f32_e32 v221, v159
	v_add_f32_e32 v159, 1.0, v181
	v_rcp_f32_e32 v228, v159
	v_add_f32_e32 v159, 1.0, v219
	v_rcp_f32_e32 v229, v159
	v_pk_fma_f32 v[224:225], v[224:225], s[8:9], 0.5 op_sel_hi:[1,0,0]
	v_pk_fma_f32 v[220:221], v[220:221], s[8:9], 0.5 op_sel_hi:[1,0,0]
	v_cvt_u32_f32_e32 v159, v225
	v_cvt_u32_f32_e32 v181, v224
	v_pk_fma_f32 v[224:225], v[226:227], s[8:9], 0.5 op_sel_hi:[1,0,0]
	v_cvt_u32_f32_sdwa v226, v221 dst_sel:WORD_1 dst_unused:UNUSED_PAD src0_sel:DWORD
	v_cvt_u32_f32_e32 v219, v224
	v_cvt_u32_f32_e32 v224, v225
	v_cvt_u32_f32_sdwa v225, v220 dst_sel:WORD_1 dst_unused:UNUSED_PAD src0_sel:DWORD
	v_pk_fma_f32 v[220:221], v[228:229], s[8:9], 0.5 op_sel_hi:[1,0,0]
	v_lshlrev_b32_e32 v219, 8, v219
	v_cvt_u32_f32_sdwa v220, v220 dst_sel:BYTE_3 dst_unused:UNUSED_PAD src0_sel:DWORD
	v_cvt_u32_f32_sdwa v221, v221 dst_sel:BYTE_3 dst_unused:UNUSED_PAD src0_sel:DWORD
	v_lshlrev_b32_e32 v224, 8, v224
	v_or_b32_e32 v159, v224, v159
	v_or_b32_e32 v181, v219, v181
	v_or_b32_e32 v159, v159, v226
	v_or_b32_e32 v181, v181, v225
	v_or_b32_e32 v221, v159, v221
	v_or_b32_e32 v220, v181, v220
	v_lshl_add_u64 v[222:223], v[222:223], 0, v[184:185]
	global_store_dwordx2 v[222:223], v[220:221], off nt
	v_pk_mul_f32 v[222:223], v[86:87], v[150:151] op_sel_hi:[1,0]
	v_pk_mul_f32 v[224:225], v[78:79], v[150:151] op_sel_hi:[1,0]
	v_mul_f32_e32 v159, 0xbfb8aa3b, v222
	v_exp_f32_e32 v159, v159
	v_mul_f32_e32 v181, 0xbfb8aa3b, v224
	v_exp_f32_e32 v181, v181
	v_mul_f32_e32 v219, 0xbfb8aa3b, v225
	v_add_f32_e32 v159, 1.0, v159
	v_rcp_f32_e32 v222, v159
	v_add_f32_e32 v159, 1.0, v181
	v_mul_f32_e32 v181, 0xbfb8aa3b, v223
	v_exp_f32_e32 v181, v181
	v_exp_f32_e32 v219, v219
	v_pk_mul_f32 v[220:221], v[88:89], v[150:151] op_sel_hi:[1,0]
	v_pk_mul_f32 v[226:227], v[80:81], v[150:151] op_sel_hi:[1,0]
	v_rcp_f32_e32 v223, v159
	v_add_f32_e32 v159, 1.0, v181
	v_mul_f32_e32 v181, 0xbfb8aa3b, v220
	v_rcp_f32_e32 v224, v159
	v_add_f32_e32 v159, 1.0, v219
	v_exp_f32_e32 v181, v181
	v_mul_f32_e32 v219, 0xbfb8aa3b, v226
	v_exp_f32_e32 v219, v219
	v_rcp_f32_e32 v225, v159
	v_add_f32_e32 v159, 1.0, v181
	v_mul_f32_e32 v181, 0xbfb8aa3b, v221
	v_rcp_f32_e32 v220, v159
	v_add_f32_e32 v159, 1.0, v219
	v_exp_f32_e32 v181, v181
	v_mul_f32_e32 v219, 0xbfb8aa3b, v227
	v_exp_f32_e32 v219, v219
	v_rcp_f32_e32 v221, v159
	v_add_f32_e32 v159, 1.0, v181
	v_rcp_f32_e32 v226, v159
	v_add_f32_e32 v159, 1.0, v219
	v_pk_fma_f32 v[222:223], v[222:223], s[8:9], 0.5 op_sel_hi:[1,0,0]
	v_rcp_f32_e32 v227, v159
	v_cvt_u32_f32_e32 v159, v223
	v_cvt_u32_f32_e32 v181, v222
	v_pk_fma_f32 v[222:223], v[224:225], s[8:9], 0.5 op_sel_hi:[1,0,0]
	v_pk_fma_f32 v[220:221], v[220:221], s[8:9], 0.5 op_sel_hi:[1,0,0]
	v_cvt_u32_f32_e32 v219, v222
	v_cvt_u32_f32_e32 v222, v223
	v_cvt_u32_f32_sdwa v223, v220 dst_sel:WORD_1 dst_unused:UNUSED_PAD src0_sel:DWORD
	v_cvt_u32_f32_sdwa v224, v221 dst_sel:WORD_1 dst_unused:UNUSED_PAD src0_sel:DWORD
	v_pk_fma_f32 v[220:221], v[226:227], s[8:9], 0.5 op_sel_hi:[1,0,0]
	v_lshlrev_b32_e32 v219, 8, v219
	v_cvt_u32_f32_sdwa v220, v220 dst_sel:BYTE_3 dst_unused:UNUSED_PAD src0_sel:DWORD
; __device__ __forceinline__ float sigmoid_f(float x) { return __builtin_amdgcn_rcpf(1.0f + __builtin_amdgcn_exp2f(-1.4426950409f * x)); }
;     __device__ __forceinline__ void body_gate(f32x4 (&acc)[2][2][4][2], const Unit& u, int wr, int wc, int fr, int fq, int gbase, const float (&rsv)[2][4]) const {
;         EPI_ROWS_BEGIN
;             const float rs = rsv[ai][m];
; #pragma unroll
;             for (int bj = 0; bj < 2; ++bj) { if (u.half != 0 && bj == 1) continue;
;                 const int gcol = gbase + (bj + (u.half == 2 ? 1 : 0)) * 128 + wc * 32 + 8 * fq;
;                 f32x4 v0 = acc[ai][bj][m][0] * rs, v1 = acc[ai][bj][m][1] * rs;
; #pragma unroll
;                 for (int j = 0; j < 4; ++j) { v0[j] = sigmoid_f(v0[j]); v1[j] = sigmoid_f(v1[j]); }
;                 u32x2 w; w.x = pk_unorm8(v0); w.y = pk_unorm8(v1);
;                 *(u32x2*)((unsigned char*)P + (size_t)row * ROWB + GATE_B0 + gcol) = w;
;             }
;         EPI_END
;     }
	v_cvt_u32_f32_sdwa v221, v221 dst_sel:BYTE_3 dst_unused:UNUSED_PAD src0_sel:DWORD
	v_lshlrev_b32_e32 v222, 8, v222
	v_or_b32_e32 v181, v219, v181
	v_or_b32_e32 v159, v222, v159
	v_or_b32_e32 v181, v181, v223
	v_mad_i64_i32 v[222:223], s[4:5], v157, s33, v[186:187]
	v_or_b32_e32 v159, v159, v224
	v_lshl_add_u64 v[222:223], v[222:223], 0, s[64:65]
	v_or_b32_e32 v221, v159, v221
	v_or_b32_e32 v220, v181, v220
	v_lshl_add_u64 v[224:225], v[222:223], 0, v[182:183]
	global_store_dwordx2 v[224:225], v[220:221], off nt
	v_pk_mul_f32 v[224:225], v[70:71], v[150:151] op_sel_hi:[1,0]
	v_pk_mul_f32 v[226:227], v[66:67], v[150:151] op_sel_hi:[1,0]
	v_mul_f32_e32 v159, 0xbfb8aa3b, v224
	v_exp_f32_e32 v159, v159
	v_mul_f32_e32 v181, 0xbfb8aa3b, v226
	v_exp_f32_e32 v181, v181
	v_mul_f32_e32 v219, 0xbfb8aa3b, v227
	v_add_f32_e32 v159, 1.0, v159
	v_rcp_f32_e32 v224, v159
	v_add_f32_e32 v159, 1.0, v181
	v_mul_f32_e32 v181, 0xbfb8aa3b, v225
	v_exp_f32_e32 v181, v181
	v_exp_f32_e32 v219, v219
	v_pk_mul_f32 v[220:221], v[72:73], v[150:151] op_sel_hi:[1,0]
	v_pk_mul_f32 v[228:229], v[68:69], v[150:151] op_sel_hi:[1,0]
	v_rcp_f32_e32 v225, v159
	v_add_f32_e32 v159, 1.0, v181
	v_mul_f32_e32 v181, 0xbfb8aa3b, v220
	v_rcp_f32_e32 v226, v159
	v_add_f32_e32 v159, 1.0, v219
	v_exp_f32_e32 v181, v181
	v_mul_f32_e32 v219, 0xbfb8aa3b, v228
	v_exp_f32_e32 v219, v219
	v_rcp_f32_e32 v227, v159
	v_add_f32_e32 v159, 1.0, v181
	v_mul_f32_e32 v181, 0xbfb8aa3b, v221
	v_rcp_f32_e32 v220, v159
	v_add_f32_e32 v159, 1.0, v219
	v_exp_f32_e32 v181, v181
	v_mul_f32_e32 v219, 0xbfb8aa3b, v229
	v_exp_f32_e32 v219, v219
	v_rcp_f32_e32 v221, v159
	v_add_f32_e32 v159, 1.0, v181
	v_rcp_f32_e32 v228, v159
	v_add_f32_e32 v159, 1.0, v219
	v_rcp_f32_e32 v229, v159
	v_pk_fma_f32 v[224:225], v[224:225], s[8:9], 0.5 op_sel_hi:[1,0,0]
	v_pk_fma_f32 v[220:221], v[220:221], s[8:9], 0.5 op_sel_hi:[1,0,0]
	v_cvt_u32_f32_e32 v159, v225
	v_cvt_u32_f32_e32 v181, v224
	v_pk_fma_f32 v[224:225], v[226:227], s[8:9], 0.5 op_sel_hi:[1,0,0]
	v_cvt_u32_f32_sdwa v226, v221 dst_sel:WORD_1 dst_unused:UNUSED_PAD src0_sel:DWORD
	v_cvt_u32_f32_e32 v219, v224
	v_cvt_u32_f32_e32 v224, v225
	v_cvt_u32_f32_sdwa v225, v220 dst_sel:WORD_1 dst_unused:UNUSED_PAD src0_sel:DWORD
	v_pk_fma_f32 v[220:221], v[228:229], s[8:9], 0.5 op_sel_hi:[1,0,0]
	v_lshlrev_b32_e32 v219, 8, v219
	v_cvt_u32_f32_sdwa v220, v220 dst_sel:BYTE_3 dst_unused:UNUSED_PAD src0_sel:DWORD
	v_cvt_u32_f32_sdwa v221, v221 dst_sel:BYTE_3 dst_unused:UNUSED_PAD src0_sel:DWORD
	v_lshlrev_b32_e32 v224, 8, v224
	v_or_b32_e32 v159, v224, v159
	v_or_b32_e32 v181, v219, v181
	v_or_b32_e32 v159, v159, v226
	v_or_b32_e32 v181, v181, v225
	v_or_b32_e32 v221, v159, v221
	v_or_b32_e32 v220, v181, v220
	v_lshl_add_u64 v[222:223], v[222:223], 0, v[184:185]
	global_store_dwordx2 v[222:223], v[220:221], off nt
	v_pk_mul_f32 v[222:223], v[62:63], v[148:149] op_sel_hi:[1,0]
	v_pk_mul_f32 v[224:225], v[58:59], v[148:149] op_sel_hi:[1,0]
	v_mul_f32_e32 v159, 0xbfb8aa3b, v222
	v_exp_f32_e32 v159, v159
	v_mul_f32_e32 v181, 0xbfb8aa3b, v224
	v_exp_f32_e32 v181, v181
	v_mul_f32_e32 v219, 0xbfb8aa3b, v225
	v_add_f32_e32 v159, 1.0, v159
	v_rcp_f32_e32 v222, v159
	v_add_f32_e32 v159, 1.0, v181
	v_mul_f32_e32 v181, 0xbfb8aa3b, v223
	v_exp_f32_e32 v181, v181
	v_exp_f32_e32 v219, v219
	v_pk_mul_f32 v[220:221], v[64:65], v[148:149] op_sel_hi:[1,0]
	v_pk_mul_f32 v[226:227], v[60:61], v[148:149] op_sel_hi:[1,0]
	v_rcp_f32_e32 v223, v159
	v_add_f32_e32 v159, 1.0, v181
	v_mul_f32_e32 v181, 0xbfb8aa3b, v220
	v_rcp_f32_e32 v224, v159
	v_add_f32_e32 v159, 1.0, v219
	v_exp_f32_e32 v181, v181
	v_mul_f32_e32 v219, 0xbfb8aa3b, v226
	v_exp_f32_e32 v219, v219
	v_rcp_f32_e32 v225, v159
	v_add_f32_e32 v159, 1.0, v181
	v_mul_f32_e32 v181, 0xbfb8aa3b, v221
	v_rcp_f32_e32 v220, v159
	v_add_f32_e32 v159, 1.0, v219
	v_exp_f32_e32 v181, v181
	v_mul_f32_e32 v219, 0xbfb8aa3b, v227
	v_exp_f32_e32 v219, v219
	v_rcp_f32_e32 v221, v159
	v_add_f32_e32 v159, 1.0, v181
	v_rcp_f32_e32 v226, v159
	v_add_f32_e32 v159, 1.0, v219
	v_pk_fma_f32 v[222:223], v[222:223], s[8:9], 0.5 op_sel_hi:[1,0,0]
	v_rcp_f32_e32 v227, v159
	v_cvt_u32_f32_e32 v159, v223
	v_cvt_u32_f32_e32 v181, v222
	v_pk_fma_f32 v[222:223], v[224:225], s[8:9], 0.5 op_sel_hi:[1,0,0]
	v_pk_fma_f32 v[220:221], v[220:221], s[8:9], 0.5 op_sel_hi:[1,0,0]
	v_cvt_u32_f32_e32 v219, v222
	v_cvt_u32_f32_e32 v222, v223
	v_cvt_u32_f32_sdwa v223, v220 dst_sel:WORD_1 dst_unused:UNUSED_PAD src0_sel:DWORD
	v_cvt_u32_f32_sdwa v224, v221 dst_sel:WORD_1 dst_unused:UNUSED_PAD src0_sel:DWORD
	v_pk_fma_f32 v[220:221], v[226:227], s[8:9], 0.5 op_sel_hi:[1,0,0]
	v_lshlrev_b32_e32 v219, 8, v219
	v_cvt_u32_f32_sdwa v220, v220 dst_sel:BYTE_3 dst_unused:UNUSED_PAD src0_sel:DWORD
	v_cvt_u32_f32_sdwa v221, v221 dst_sel:BYTE_3 dst_unused:UNUSED_PAD src0_sel:DWORD
	v_lshlrev_b32_e32 v222, 8, v222
	v_or_b32_e32 v181, v219, v181
	v_or_b32_e32 v159, v222, v159
	v_or_b32_e32 v181, v181, v223
	v_mad_i64_i32 v[222:223], s[4:5], v155, s33, v[186:187]
	v_or_b32_e32 v159, v159, v224
	v_lshl_add_u64 v[222:223], v[222:223], 0, s[64:65]
	v_or_b32_e32 v221, v159, v221
	v_or_b32_e32 v220, v181, v220
	v_lshl_add_u64 v[224:225], v[222:223], 0, v[182:183]
	global_store_dwordx2 v[224:225], v[220:221], off nt
	v_pk_mul_f32 v[224:225], v[50:51], v[148:149] op_sel_hi:[1,0]
	v_pk_mul_f32 v[226:227], v[42:43], v[148:149] op_sel_hi:[1,0]
	v_mul_f32_e32 v159, 0xbfb8aa3b, v224
	v_exp_f32_e32 v159, v159
	v_mul_f32_e32 v181, 0xbfb8aa3b, v226
	v_exp_f32_e32 v181, v181
	v_mul_f32_e32 v219, 0xbfb8aa3b, v227
	v_add_f32_e32 v159, 1.0, v159
	v_rcp_f32_e32 v224, v159
	v_add_f32_e32 v159, 1.0, v181
	v_mul_f32_e32 v181, 0xbfb8aa3b, v225
; __device__ __forceinline__ float sigmoid_f(float x) { return __builtin_amdgcn_rcpf(1.0f + __builtin_amdgcn_exp2f(-1.4426950409f * x)); }
;     __device__ __forceinline__ void body_gate(f32x4 (&acc)[2][2][4][2], const Unit& u, int wr, int wc, int fr, int fq, int gbase, const float (&rsv)[2][4]) const {
;         EPI_ROWS_BEGIN
;             const float rs = rsv[ai][m];
; #pragma unroll
;             for (int bj = 0; bj < 2; ++bj) { if (u.half != 0 && bj == 1) continue;
;                 const int gcol = gbase + (bj + (u.half == 2 ? 1 : 0)) * 128 + wc * 32 + 8 * fq;
;                 f32x4 v0 = acc[ai][bj][m][0] * rs, v1 = acc[ai][bj][m][1] * rs;
; #pragma unroll
;                 for (int j = 0; j < 4; ++j) { v0[j] = sigmoid_f(v0[j]); v1[j] = sigmoid_f(v1[j]); }
;                 u32x2 w; w.x = pk_unorm8(v0); w.y = pk_unorm8(v1);
;                 *(u32x2*)((unsigned char*)P + (size_t)row * ROWB + GATE_B0 + gcol) = w;
;             }
;         EPI_END
;     }
	v_exp_f32_e32 v181, v181
	v_exp_f32_e32 v219, v219
	v_pk_mul_f32 v[220:221], v[52:53], v[148:149] op_sel_hi:[1,0]
	v_pk_mul_f32 v[228:229], v[44:45], v[148:149] op_sel_hi:[1,0]
	v_rcp_f32_e32 v225, v159
	v_add_f32_e32 v159, 1.0, v181
	v_mul_f32_e32 v181, 0xbfb8aa3b, v220
	v_rcp_f32_e32 v226, v159
	v_add_f32_e32 v159, 1.0, v219
	v_exp_f32_e32 v181, v181
	v_mul_f32_e32 v219, 0xbfb8aa3b, v228
	v_exp_f32_e32 v219, v219
	v_rcp_f32_e32 v227, v159
	v_add_f32_e32 v159, 1.0, v181
	v_mul_f32_e32 v181, 0xbfb8aa3b, v221
	v_rcp_f32_e32 v220, v159
	v_add_f32_e32 v159, 1.0, v219
	v_exp_f32_e32 v181, v181
	v_mul_f32_e32 v219, 0xbfb8aa3b, v229
	v_exp_f32_e32 v219, v219
	v_rcp_f32_e32 v221, v159
	v_add_f32_e32 v159, 1.0, v181
	v_rcp_f32_e32 v228, v159
	v_add_f32_e32 v159, 1.0, v219
	v_rcp_f32_e32 v229, v159
	v_pk_fma_f32 v[224:225], v[224:225], s[8:9], 0.5 op_sel_hi:[1,0,0]
	v_pk_fma_f32 v[220:221], v[220:221], s[8:9], 0.5 op_sel_hi:[1,0,0]
	v_cvt_u32_f32_e32 v159, v225
	v_cvt_u32_f32_e32 v181, v224
	v_pk_fma_f32 v[224:225], v[226:227], s[8:9], 0.5 op_sel_hi:[1,0,0]
	v_cvt_u32_f32_sdwa v226, v221 dst_sel:WORD_1 dst_unused:UNUSED_PAD src0_sel:DWORD
	v_cvt_u32_f32_e32 v219, v224
	v_cvt_u32_f32_e32 v224, v225
	v_cvt_u32_f32_sdwa v225, v220 dst_sel:WORD_1 dst_unused:UNUSED_PAD src0_sel:DWORD
	v_pk_fma_f32 v[220:221], v[228:229], s[8:9], 0.5 op_sel_hi:[1,0,0]
	v_lshlrev_b32_e32 v219, 8, v219
	v_cvt_u32_f32_sdwa v220, v220 dst_sel:BYTE_3 dst_unused:UNUSED_PAD src0_sel:DWORD
	v_cvt_u32_f32_sdwa v221, v221 dst_sel:BYTE_3 dst_unused:UNUSED_PAD src0_sel:DWORD
	v_lshlrev_b32_e32 v224, 8, v224
	v_or_b32_e32 v159, v224, v159
	v_or_b32_e32 v181, v219, v181
	v_or_b32_e32 v159, v159, v226
	v_or_b32_e32 v181, v181, v225
	v_or_b32_e32 v221, v159, v221
	v_or_b32_e32 v220, v181, v220
	v_lshl_add_u64 v[222:223], v[222:223], 0, v[184:185]
	global_store_dwordx2 v[222:223], v[220:221], off nt
	v_pk_mul_f32 v[222:223], v[54:55], v[146:147] op_sel_hi:[1,0]
	v_pk_mul_f32 v[224:225], v[46:47], v[146:147] op_sel_hi:[1,0]
	v_mul_f32_e32 v159, 0xbfb8aa3b, v222
	v_exp_f32_e32 v159, v159
	v_mul_f32_e32 v181, 0xbfb8aa3b, v224
	v_exp_f32_e32 v181, v181
	v_mul_f32_e32 v219, 0xbfb8aa3b, v225
	v_add_f32_e32 v159, 1.0, v159
	v_rcp_f32_e32 v222, v159
	v_add_f32_e32 v159, 1.0, v181
	v_mul_f32_e32 v181, 0xbfb8aa3b, v223
	v_exp_f32_e32 v181, v181
	v_exp_f32_e32 v219, v219
	v_pk_mul_f32 v[220:221], v[56:57], v[146:147] op_sel_hi:[1,0]
	v_pk_mul_f32 v[226:227], v[48:49], v[146:147] op_sel_hi:[1,0]
	v_rcp_f32_e32 v223, v159
	v_add_f32_e32 v159, 1.0, v181
	v_mul_f32_e32 v181, 0xbfb8aa3b, v220
	v_rcp_f32_e32 v224, v159
	v_add_f32_e32 v159, 1.0, v219
	v_exp_f32_e32 v181, v181
	v_mul_f32_e32 v219, 0xbfb8aa3b, v226
	v_exp_f32_e32 v219, v219
	v_rcp_f32_e32 v225, v159
	v_add_f32_e32 v159, 1.0, v181
	v_mul_f32_e32 v181, 0xbfb8aa3b, v221
	v_rcp_f32_e32 v220, v159
	v_add_f32_e32 v159, 1.0, v219
	v_exp_f32_e32 v181, v181
	v_mul_f32_e32 v219, 0xbfb8aa3b, v227
	v_exp_f32_e32 v219, v219
	v_rcp_f32_e32 v221, v159
	v_add_f32_e32 v159, 1.0, v181
	v_rcp_f32_e32 v226, v159
	v_add_f32_e32 v159, 1.0, v219
	v_pk_fma_f32 v[222:223], v[222:223], s[8:9], 0.5 op_sel_hi:[1,0,0]
	v_rcp_f32_e32 v227, v159
	v_cvt_u32_f32_e32 v159, v223
	v_cvt_u32_f32_e32 v181, v222
	v_pk_fma_f32 v[222:223], v[224:225], s[8:9], 0.5 op_sel_hi:[1,0,0]
	v_pk_fma_f32 v[220:221], v[220:221], s[8:9], 0.5 op_sel_hi:[1,0,0]
	v_cvt_u32_f32_e32 v219, v222
	v_cvt_u32_f32_e32 v222, v223
	v_cvt_u32_f32_sdwa v223, v220 dst_sel:WORD_1 dst_unused:UNUSED_PAD src0_sel:DWORD
	v_cvt_u32_f32_sdwa v224, v221 dst_sel:WORD_1 dst_unused:UNUSED_PAD src0_sel:DWORD
	v_pk_fma_f32 v[220:221], v[226:227], s[8:9], 0.5 op_sel_hi:[1,0,0]
	v_lshlrev_b32_e32 v219, 8, v219
	v_cvt_u32_f32_sdwa v220, v220 dst_sel:BYTE_3 dst_unused:UNUSED_PAD src0_sel:DWORD
	v_cvt_u32_f32_sdwa v221, v221 dst_sel:BYTE_3 dst_unused:UNUSED_PAD src0_sel:DWORD
	v_lshlrev_b32_e32 v222, 8, v222
	v_or_b32_e32 v181, v219, v181
	v_or_b32_e32 v159, v222, v159
	v_or_b32_e32 v181, v181, v223
	v_mad_i64_i32 v[222:223], s[4:5], v153, s33, v[186:187]
	v_or_b32_e32 v159, v159, v224
	v_lshl_add_u64 v[222:223], v[222:223], 0, s[64:65]
	v_or_b32_e32 v221, v159, v221
	v_or_b32_e32 v220, v181, v220
	v_lshl_add_u64 v[224:225], v[222:223], 0, v[182:183]
	global_store_dwordx2 v[224:225], v[220:221], off nt
	v_pk_mul_f32 v[224:225], v[34:35], v[146:147] op_sel_hi:[1,0]
	v_pk_mul_f32 v[226:227], v[26:27], v[146:147] op_sel_hi:[1,0]
	v_mul_f32_e32 v159, 0xbfb8aa3b, v224
	v_exp_f32_e32 v159, v159
	v_mul_f32_e32 v181, 0xbfb8aa3b, v226
	v_exp_f32_e32 v181, v181
	v_mul_f32_e32 v219, 0xbfb8aa3b, v227
	v_add_f32_e32 v159, 1.0, v159
	v_rcp_f32_e32 v224, v159
	v_add_f32_e32 v159, 1.0, v181
	v_mul_f32_e32 v181, 0xbfb8aa3b, v225
	v_exp_f32_e32 v181, v181
	v_exp_f32_e32 v219, v219
	v_pk_mul_f32 v[220:221], v[36:37], v[146:147] op_sel_hi:[1,0]
	v_pk_mul_f32 v[228:229], v[28:29], v[146:147] op_sel_hi:[1,0]
	v_rcp_f32_e32 v225, v159
	v_add_f32_e32 v159, 1.0, v181
	v_mul_f32_e32 v181, 0xbfb8aa3b, v220
	v_rcp_f32_e32 v226, v159
	v_add_f32_e32 v159, 1.0, v219
	v_exp_f32_e32 v181, v181
	v_mul_f32_e32 v219, 0xbfb8aa3b, v228
	v_exp_f32_e32 v219, v219
	v_rcp_f32_e32 v227, v159
	v_add_f32_e32 v159, 1.0, v181
	v_mul_f32_e32 v181, 0xbfb8aa3b, v221
	v_rcp_f32_e32 v220, v159
	v_add_f32_e32 v159, 1.0, v219
	v_exp_f32_e32 v181, v181
	v_mul_f32_e32 v219, 0xbfb8aa3b, v229
	v_exp_f32_e32 v219, v219
	v_rcp_f32_e32 v221, v159
	v_add_f32_e32 v159, 1.0, v181
	v_rcp_f32_e32 v228, v159
	v_add_f32_e32 v159, 1.0, v219
	v_rcp_f32_e32 v229, v159
	v_pk_fma_f32 v[224:225], v[224:225], s[8:9], 0.5 op_sel_hi:[1,0,0]
	v_pk_fma_f32 v[220:221], v[220:221], s[8:9], 0.5 op_sel_hi:[1,0,0]
; __device__ __forceinline__ float sigmoid_f(float x) { return __builtin_amdgcn_rcpf(1.0f + __builtin_amdgcn_exp2f(-1.4426950409f * x)); }
;     __device__ __forceinline__ void body_gate(f32x4 (&acc)[2][2][4][2], const Unit& u, int wr, int wc, int fr, int fq, int gbase, const float (&rsv)[2][4]) const {
;         EPI_ROWS_BEGIN
;             const float rs = rsv[ai][m];
; #pragma unroll
;             for (int bj = 0; bj < 2; ++bj) { if (u.half != 0 && bj == 1) continue;
;                 const int gcol = gbase + (bj + (u.half == 2 ? 1 : 0)) * 128 + wc * 32 + 8 * fq;
;                 f32x4 v0 = acc[ai][bj][m][0] * rs, v1 = acc[ai][bj][m][1] * rs;
; #pragma unroll
;                 for (int j = 0; j < 4; ++j) { v0[j] = sigmoid_f(v0[j]); v1[j] = sigmoid_f(v1[j]); }
;                 u32x2 w; w.x = pk_unorm8(v0); w.y = pk_unorm8(v1);
;                 *(u32x2*)((unsigned char*)P + (size_t)row * ROWB + GATE_B0 + gcol) = w;
;             }
;         EPI_END
;     }
	v_cvt_u32_f32_e32 v159, v225
	v_cvt_u32_f32_e32 v181, v224
	v_pk_fma_f32 v[224:225], v[226:227], s[8:9], 0.5 op_sel_hi:[1,0,0]
	v_cvt_u32_f32_sdwa v226, v221 dst_sel:WORD_1 dst_unused:UNUSED_PAD src0_sel:DWORD
	v_cvt_u32_f32_e32 v219, v224
	v_cvt_u32_f32_e32 v224, v225
	v_cvt_u32_f32_sdwa v225, v220 dst_sel:WORD_1 dst_unused:UNUSED_PAD src0_sel:DWORD
	v_pk_fma_f32 v[220:221], v[228:229], s[8:9], 0.5 op_sel_hi:[1,0,0]
	v_lshlrev_b32_e32 v219, 8, v219
	v_cvt_u32_f32_sdwa v220, v220 dst_sel:BYTE_3 dst_unused:UNUSED_PAD src0_sel:DWORD
	v_cvt_u32_f32_sdwa v221, v221 dst_sel:BYTE_3 dst_unused:UNUSED_PAD src0_sel:DWORD
	v_lshlrev_b32_e32 v224, 8, v224
	v_or_b32_e32 v159, v224, v159
	v_or_b32_e32 v181, v219, v181
	v_or_b32_e32 v159, v159, v226
	v_or_b32_e32 v181, v181, v225
	v_or_b32_e32 v221, v159, v221
	v_or_b32_e32 v220, v181, v220
	v_lshl_add_u64 v[222:223], v[222:223], 0, v[184:185]
	global_store_dwordx2 v[222:223], v[220:221], off nt
	v_pk_mul_f32 v[222:223], v[38:39], v[144:145] op_sel_hi:[1,0]
	v_pk_mul_f32 v[224:225], v[30:31], v[144:145] op_sel_hi:[1,0]
	v_mul_f32_e32 v159, 0xbfb8aa3b, v222
	v_exp_f32_e32 v159, v159
	v_mul_f32_e32 v181, 0xbfb8aa3b, v224
	v_exp_f32_e32 v181, v181
	v_mul_f32_e32 v219, 0xbfb8aa3b, v225
	v_add_f32_e32 v159, 1.0, v159
	v_rcp_f32_e32 v222, v159
	v_add_f32_e32 v159, 1.0, v181
	v_mul_f32_e32 v181, 0xbfb8aa3b, v223
	v_exp_f32_e32 v181, v181
	v_exp_f32_e32 v219, v219
	v_pk_mul_f32 v[220:221], v[40:41], v[144:145] op_sel_hi:[1,0]
	v_pk_mul_f32 v[226:227], v[32:33], v[144:145] op_sel_hi:[1,0]
	v_rcp_f32_e32 v223, v159
	v_add_f32_e32 v159, 1.0, v181
	v_mul_f32_e32 v181, 0xbfb8aa3b, v220
	v_rcp_f32_e32 v224, v159
	v_add_f32_e32 v159, 1.0, v219
	v_exp_f32_e32 v181, v181
	v_mul_f32_e32 v219, 0xbfb8aa3b, v226
	v_exp_f32_e32 v219, v219
	v_rcp_f32_e32 v225, v159
	v_add_f32_e32 v159, 1.0, v181
	v_mul_f32_e32 v181, 0xbfb8aa3b, v221
	v_rcp_f32_e32 v220, v159
	v_add_f32_e32 v159, 1.0, v219
	v_exp_f32_e32 v181, v181
	v_mul_f32_e32 v219, 0xbfb8aa3b, v227
	v_exp_f32_e32 v219, v219
	v_rcp_f32_e32 v221, v159
	v_add_f32_e32 v159, 1.0, v181
	v_rcp_f32_e32 v226, v159
	v_add_f32_e32 v159, 1.0, v219
	v_pk_fma_f32 v[222:223], v[222:223], s[8:9], 0.5 op_sel_hi:[1,0,0]
	v_rcp_f32_e32 v227, v159
	v_cvt_u32_f32_e32 v159, v223
	v_cvt_u32_f32_e32 v181, v222
	v_pk_fma_f32 v[222:223], v[224:225], s[8:9], 0.5 op_sel_hi:[1,0,0]
	v_pk_fma_f32 v[220:221], v[220:221], s[8:9], 0.5 op_sel_hi:[1,0,0]
	v_cvt_u32_f32_e32 v219, v222
	v_cvt_u32_f32_e32 v222, v223
	v_cvt_u32_f32_sdwa v223, v220 dst_sel:WORD_1 dst_unused:UNUSED_PAD src0_sel:DWORD
	v_cvt_u32_f32_sdwa v224, v221 dst_sel:WORD_1 dst_unused:UNUSED_PAD src0_sel:DWORD
	v_pk_fma_f32 v[220:221], v[226:227], s[8:9], 0.5 op_sel_hi:[1,0,0]
	v_lshlrev_b32_e32 v219, 8, v219
	v_cvt_u32_f32_sdwa v220, v220 dst_sel:BYTE_3 dst_unused:UNUSED_PAD src0_sel:DWORD
	v_cvt_u32_f32_sdwa v221, v221 dst_sel:BYTE_3 dst_unused:UNUSED_PAD src0_sel:DWORD
	v_lshlrev_b32_e32 v222, 8, v222
	v_or_b32_e32 v181, v219, v181
	v_or_b32_e32 v159, v222, v159
	v_or_b32_e32 v181, v181, v223
	v_mad_i64_i32 v[222:223], s[4:5], v151, s33, v[186:187]
	v_or_b32_e32 v159, v159, v224
	v_lshl_add_u64 v[222:223], v[222:223], 0, s[64:65]
	v_or_b32_e32 v221, v159, v221
	v_or_b32_e32 v220, v181, v220
	v_lshl_add_u64 v[224:225], v[222:223], 0, v[182:183]
	global_store_dwordx2 v[224:225], v[220:221], off nt
	v_pk_mul_f32 v[224:225], v[18:19], v[144:145] op_sel_hi:[1,0]
	v_pk_mul_f32 v[226:227], v[10:11], v[144:145] op_sel_hi:[1,0]
	v_mul_f32_e32 v159, 0xbfb8aa3b, v224
	v_exp_f32_e32 v159, v159
	v_mul_f32_e32 v181, 0xbfb8aa3b, v226
	v_exp_f32_e32 v181, v181
	v_mul_f32_e32 v219, 0xbfb8aa3b, v227
	v_add_f32_e32 v159, 1.0, v159
	v_rcp_f32_e32 v224, v159
	v_add_f32_e32 v159, 1.0, v181
	v_mul_f32_e32 v181, 0xbfb8aa3b, v225
	v_exp_f32_e32 v181, v181
	v_exp_f32_e32 v219, v219
	v_pk_mul_f32 v[220:221], v[20:21], v[144:145] op_sel_hi:[1,0]
	v_pk_mul_f32 v[228:229], v[12:13], v[144:145] op_sel_hi:[1,0]
	v_rcp_f32_e32 v225, v159
	v_add_f32_e32 v159, 1.0, v181
	v_mul_f32_e32 v181, 0xbfb8aa3b, v220
	v_rcp_f32_e32 v226, v159
	v_add_f32_e32 v159, 1.0, v219
	v_exp_f32_e32 v181, v181
	v_mul_f32_e32 v219, 0xbfb8aa3b, v228
	v_exp_f32_e32 v219, v219
	v_rcp_f32_e32 v227, v159
	v_add_f32_e32 v159, 1.0, v181
	v_mul_f32_e32 v181, 0xbfb8aa3b, v221
	v_rcp_f32_e32 v220, v159
	v_add_f32_e32 v159, 1.0, v219
	v_exp_f32_e32 v181, v181
	v_mul_f32_e32 v219, 0xbfb8aa3b, v229
	v_exp_f32_e32 v219, v219
	v_rcp_f32_e32 v221, v159
	v_add_f32_e32 v159, 1.0, v181
	v_rcp_f32_e32 v228, v159
	v_add_f32_e32 v159, 1.0, v219
	v_rcp_f32_e32 v229, v159
	v_pk_fma_f32 v[224:225], v[224:225], s[8:9], 0.5 op_sel_hi:[1,0,0]
	v_pk_fma_f32 v[220:221], v[220:221], s[8:9], 0.5 op_sel_hi:[1,0,0]
	v_cvt_u32_f32_e32 v159, v225
	v_cvt_u32_f32_e32 v181, v224
	v_pk_fma_f32 v[224:225], v[226:227], s[8:9], 0.5 op_sel_hi:[1,0,0]
	v_cvt_u32_f32_sdwa v226, v221 dst_sel:WORD_1 dst_unused:UNUSED_PAD src0_sel:DWORD
	v_cvt_u32_f32_e32 v219, v224
	v_cvt_u32_f32_e32 v224, v225
	v_cvt_u32_f32_sdwa v225, v220 dst_sel:WORD_1 dst_unused:UNUSED_PAD src0_sel:DWORD
	v_pk_fma_f32 v[220:221], v[228:229], s[8:9], 0.5 op_sel_hi:[1,0,0]
	v_lshlrev_b32_e32 v219, 8, v219
; __device__ __forceinline__ float sigmoid_f(float x) { return __builtin_amdgcn_rcpf(1.0f + __builtin_amdgcn_exp2f(-1.4426950409f * x)); }
;     __device__ __forceinline__ void body_gate(f32x4 (&acc)[2][2][4][2], const Unit& u, int wr, int wc, int fr, int fq, int gbase, const float (&rsv)[2][4]) const {
;         EPI_ROWS_BEGIN
;             const float rs = rsv[ai][m];
; #pragma unroll
;             for (int bj = 0; bj < 2; ++bj) { if (u.half != 0 && bj == 1) continue;
;                 const int gcol = gbase + (bj + (u.half == 2 ? 1 : 0)) * 128 + wc * 32 + 8 * fq;
;                 f32x4 v0 = acc[ai][bj][m][0] * rs, v1 = acc[ai][bj][m][1] * rs;
; #pragma unroll
;                 for (int j = 0; j < 4; ++j) { v0[j] = sigmoid_f(v0[j]); v1[j] = sigmoid_f(v1[j]); }
;                 u32x2 w; w.x = pk_unorm8(v0); w.y = pk_unorm8(v1);
;                 *(u32x2*)((unsigned char*)P + (size_t)row * ROWB + GATE_B0 + gcol) = w;
;             }
;         EPI_END
;     }
	v_cvt_u32_f32_sdwa v220, v220 dst_sel:BYTE_3 dst_unused:UNUSED_PAD src0_sel:DWORD
	v_cvt_u32_f32_sdwa v221, v221 dst_sel:BYTE_3 dst_unused:UNUSED_PAD src0_sel:DWORD
	v_lshlrev_b32_e32 v224, 8, v224
	v_or_b32_e32 v159, v224, v159
	v_or_b32_e32 v181, v219, v181
	v_or_b32_e32 v159, v159, v226
	v_or_b32_e32 v181, v181, v225
	v_or_b32_e32 v221, v159, v221
	v_or_b32_e32 v220, v181, v220
	v_lshl_add_u64 v[222:223], v[222:223], 0, v[184:185]
	global_store_dwordx2 v[222:223], v[220:221], off nt
	v_pk_mul_f32 v[222:223], v[22:23], v[142:143] op_sel_hi:[1,0]
	v_pk_mul_f32 v[224:225], v[14:15], v[142:143] op_sel_hi:[1,0]
	v_mul_f32_e32 v159, 0xbfb8aa3b, v222
	v_exp_f32_e32 v159, v159
	v_mul_f32_e32 v181, 0xbfb8aa3b, v224
	v_exp_f32_e32 v181, v181
	v_mul_f32_e32 v219, 0xbfb8aa3b, v225
	v_add_f32_e32 v159, 1.0, v159
	v_rcp_f32_e32 v222, v159
	v_add_f32_e32 v159, 1.0, v181
	v_mul_f32_e32 v181, 0xbfb8aa3b, v223
	v_exp_f32_e32 v181, v181
	v_exp_f32_e32 v219, v219
	v_pk_mul_f32 v[220:221], v[24:25], v[142:143] op_sel_hi:[1,0]
	v_pk_mul_f32 v[226:227], v[16:17], v[142:143] op_sel_hi:[1,0]
	v_rcp_f32_e32 v223, v159
	v_add_f32_e32 v159, 1.0, v181
	v_mul_f32_e32 v181, 0xbfb8aa3b, v220
	v_rcp_f32_e32 v224, v159
	v_add_f32_e32 v159, 1.0, v219
	v_exp_f32_e32 v181, v181
	v_mul_f32_e32 v219, 0xbfb8aa3b, v226
	v_exp_f32_e32 v219, v219
	v_rcp_f32_e32 v225, v159
	v_add_f32_e32 v159, 1.0, v181
	v_mul_f32_e32 v181, 0xbfb8aa3b, v221
	v_rcp_f32_e32 v220, v159
	v_add_f32_e32 v159, 1.0, v219
	v_exp_f32_e32 v181, v181
	v_mul_f32_e32 v219, 0xbfb8aa3b, v227
	v_exp_f32_e32 v219, v219
	v_rcp_f32_e32 v221, v159
	v_add_f32_e32 v159, 1.0, v181
	v_rcp_f32_e32 v226, v159
	v_add_f32_e32 v159, 1.0, v219
	v_rcp_f32_e32 v227, v159
	v_pk_fma_f32 v[222:223], v[222:223], s[8:9], 0.5 op_sel_hi:[1,0,0]
	v_pk_fma_f32 v[220:221], v[220:221], s[8:9], 0.5 op_sel_hi:[1,0,0]
	v_cvt_u32_f32_e32 v159, v223
	v_cvt_u32_f32_e32 v181, v222
	v_pk_fma_f32 v[222:223], v[224:225], s[8:9], 0.5 op_sel_hi:[1,0,0]
	v_cvt_u32_f32_sdwa v224, v221 dst_sel:WORD_1 dst_unused:UNUSED_PAD src0_sel:DWORD
	v_cvt_u32_f32_e32 v219, v222
	v_cvt_u32_f32_e32 v222, v223
	v_cvt_u32_f32_sdwa v223, v220 dst_sel:WORD_1 dst_unused:UNUSED_PAD src0_sel:DWORD
	v_pk_fma_f32 v[220:221], v[226:227], s[8:9], 0.5 op_sel_hi:[1,0,0]
	v_lshlrev_b32_e32 v219, 8, v219
	v_cvt_u32_f32_sdwa v220, v220 dst_sel:BYTE_3 dst_unused:UNUSED_PAD src0_sel:DWORD
	v_cvt_u32_f32_sdwa v221, v221 dst_sel:BYTE_3 dst_unused:UNUSED_PAD src0_sel:DWORD
	v_lshlrev_b32_e32 v222, 8, v222
	v_or_b32_e32 v159, v222, v159
	v_or_b32_e32 v181, v219, v181
	v_mad_i64_i32 v[186:187], s[4:5], v149, s33, v[186:187]
	v_or_b32_e32 v159, v159, v224
	v_or_b32_e32 v181, v181, v223
	v_lshl_add_u64 v[186:187], v[186:187], 0, s[64:65]
	v_or_b32_e32 v221, v159, v221
	v_or_b32_e32 v220, v181, v220
	v_lshl_add_u64 v[182:183], v[186:187], 0, v[182:183]
	global_store_dwordx2 v[182:183], v[220:221], off nt
	v_pk_mul_f32 v[220:221], v[6:7], v[142:143] op_sel_hi:[1,0]
	v_pk_mul_f32 v[222:223], v[2:3], v[142:143] op_sel_hi:[1,0]
	v_mul_f32_e32 v159, 0xbfb8aa3b, v220
	v_exp_f32_e32 v159, v159
	v_mul_f32_e32 v181, 0xbfb8aa3b, v222
	v_exp_f32_e32 v181, v181
	v_mul_f32_e32 v219, 0xbfb8aa3b, v223
	v_add_f32_e32 v159, 1.0, v159
	v_rcp_f32_e32 v220, v159
	v_add_f32_e32 v159, 1.0, v181
	v_mul_f32_e32 v181, 0xbfb8aa3b, v221
	v_exp_f32_e32 v181, v181
	v_pk_mul_f32 v[182:183], v[8:9], v[142:143] op_sel_hi:[1,0]
	v_exp_f32_e32 v219, v219
	v_rcp_f32_e32 v221, v159
	v_add_f32_e32 v159, 1.0, v181
	v_mul_f32_e32 v181, 0xbfb8aa3b, v182
	v_pk_mul_f32 v[224:225], v[4:5], v[142:143] op_sel_hi:[1,0]
	v_exp_f32_e32 v181, v181
	v_mul_f32_e32 v182, 0xbfb8aa3b, v224
	v_rcp_f32_e32 v222, v159
	v_add_f32_e32 v159, 1.0, v219
	v_exp_f32_e32 v219, v182
	v_rcp_f32_e32 v223, v159
	v_add_f32_e32 v159, 1.0, v181
	v_mul_f32_e32 v181, 0xbfb8aa3b, v183
	v_exp_f32_e32 v181, v181
	v_mul_f32_e32 v183, 0xbfb8aa3b, v225
	v_rcp_f32_e32 v182, v159
	v_add_f32_e32 v159, 1.0, v219
	v_exp_f32_e32 v219, v183
	v_rcp_f32_e32 v183, v159
	v_add_f32_e32 v159, 1.0, v181
	v_rcp_f32_e32 v224, v159
	v_add_f32_e32 v159, 1.0, v219
	v_rcp_f32_e32 v225, v159
	v_pk_fma_f32 v[220:221], v[220:221], s[8:9], 0.5 op_sel_hi:[1,0,0]
	v_pk_fma_f32 v[182:183], v[182:183], s[8:9], 0.5 op_sel_hi:[1,0,0]
	v_cvt_u32_f32_e32 v159, v221
	v_cvt_u32_f32_e32 v181, v220
	v_pk_fma_f32 v[220:221], v[222:223], s[8:9], 0.5 op_sel_hi:[1,0,0]
	v_cvt_u32_f32_sdwa v222, v183 dst_sel:WORD_1 dst_unused:UNUSED_PAD src0_sel:DWORD
	v_cvt_u32_f32_e32 v219, v220
	v_cvt_u32_f32_e32 v220, v221
	v_cvt_u32_f32_sdwa v221, v182 dst_sel:WORD_1 dst_unused:UNUSED_PAD src0_sel:DWORD
	v_pk_fma_f32 v[182:183], v[224:225], s[8:9], 0.5 op_sel_hi:[1,0,0]
	v_lshlrev_b32_e32 v219, 8, v219
	v_cvt_u32_f32_sdwa v182, v182 dst_sel:BYTE_3 dst_unused:UNUSED_PAD src0_sel:DWORD
	v_cvt_u32_f32_sdwa v183, v183 dst_sel:BYTE_3 dst_unused:UNUSED_PAD src0_sel:DWORD
	v_lshlrev_b32_e32 v220, 8, v220
	v_or_b32_e32 v159, v220, v159
	v_or_b32_e32 v181, v219, v181
	v_or_b32_e32 v159, v159, v222
	v_or_b32_e32 v181, v181, v221
	v_or_b32_e32 v183, v159, v183
	v_or_b32_e32 v182, v181, v182
	v_lshl_add_u64 v[184:185], v[186:187], 0, v[184:185]
	global_store_dwordx2 v[184:185], v[182:183], off nt
	s_mov_b64 s[4:5], 0

; __device__ __forceinline__ float sigmoid_f(float x) { return __builtin_amdgcn_rcpf(1.0f + __builtin_amdgcn_exp2f(-1.4426950409f * x)); }
;     __device__ __forceinline__ void body_gate(f32x4 (&acc)[2][2][4][2], const Unit& u, int wr, int wc, int fr, int fq, int gbase, const float (&rsv)[2][4]) const {
;         EPI_ROWS_BEGIN
;             const float rs = rsv[ai][m];
; #pragma unroll
;             for (int bj = 0; bj < 2; ++bj) { if (u.half != 0 && bj == 1) continue;
;                 const int gcol = gbase + (bj + (u.half == 2 ? 1 : 0)) * 128 + wc * 32 + 8 * fq;
;                 f32x4 v0 = acc[ai][bj][m][0] * rs, v1 = acc[ai][bj][m][1] * rs;
; #pragma unroll
;                 for (int j = 0; j < 4; ++j) { v0[j] = sigmoid_f(v0[j]); v1[j] = sigmoid_f(v1[j]); }
;                 u32x2 w; w.x = pk_unorm8(v0); w.y = pk_unorm8(v1);
;                 *(u32x2*)((unsigned char*)P + (size_t)row * ROWB + GATE_B0 + gcol) = w;
;             }
;         EPI_END
;     }
;     __device__ __forceinline__ void operator()(f32x4 (&acc)[2][2][4][2], const Unit& u, int wr, int wc, int fr, int fq) const {
;     ...
;         const int pn = u.pn + pn0;
;         if (pn < 8) body_pair<0>(acc, u, wr, wc, fr, fq, OQ + pn * 128, rsv);
;         else if (pn < 16) body_pair<1>(acc, u, wr, wc, fr, fq, OAB + (pn - 8) * 128, rsv);
;         else if (pn < 20) body<0>(acc, u, wr, wc, fr, fq, OBIN + (pn - 16) * 256, rsv);
;         else if (pn < 24) body<1>(acc, u, wr, wc, fr, fq, OBZ + (pn - 20) * 256, rsv);
;         else if (pn < 32) body_pair<2>(acc, u, wr, wc, fr, fq, OV + (pn - 24) * 128, rsv);
;         else if (pn < 36) body<1>(acc, u, wr, wc, fr, fq, OCZ + (pn - 32) * 256, rsv);
;         else body_gate(acc, u, wr, wc, fr, fq, (pn - 36) * 256, rsv);
.LBB0_245:
	s_cmp_gt_u32 s8, 15
	s_cbranch_scc0 .LBB0_263
	s_cmp_gt_u32 s8, 19
	s_cbranch_scc0 .LBB0_260
	s_cmp_gt_u32 s8, 23
	s_cbranch_scc0 .LBB0_257
	s_cmp_gt_u32 s8, 31
	s_cbranch_scc0 .LBB0_254
	v_pk_mul_f32 v[104:105], v[62:63], v[94:95] op_sel_hi:[1,0]
	s_lshl_b32 s9, s8, 8
	v_mul_f32_e32 v95, 0xbfb8aa3b, v104
	v_exp_f32_e32 v95, v95
	v_mad_i64_i32 v[98:99], s[4:5], v88, s33, 0
	s_cmp_gt_u32 s8, 35
	v_pk_mul_f32 v[100:101], v[64:65], v[94:95] op_sel_hi:[1,0]
	v_pk_mul_f32 v[96:97], v[60:61], v[94:95] op_sel_hi:[1,0]
	v_pk_mul_f32 v[102:103], v[58:59], v[94:95] op_sel_hi:[1,0]
	v_add_f32_e32 v95, 1.0, v95
	v_rcp_f32_e32 v106, v95
	v_lshlrev_b32_e32 v121, 3, v114
	s_mov_b64 s[4:5], -1
	v_lshl_add_u64 v[98:99], s[68:69], 0, v[98:99]
	v_mul_f32_e32 v122, 0xbfb8aa3b, v102
	v_mul_f32_e32 v120, 0xbfb8aa3b, v105
	v_mul_f32_e32 v119, 0xbfb8aa3b, v103
	v_mul_f32_e32 v118, 0xbfb8aa3b, v100
	v_mul_f32_e32 v117, 0xbfb8aa3b, v96
	v_mul_f32_e32 v116, 0xbfb8aa3b, v101
	v_mul_f32_e32 v115, 0xbfb8aa3b, v97
	s_cbranch_scc0 .LBB0_251
	v_exp_f32_e32 v95, v122
	v_exp_f32_e32 v108, v120
	v_exp_f32_e32 v109, v115
	s_mov_b32 s26, 0x437f0000
	v_add_f32_e32 v95, 1.0, v95
	v_rcp_f32_e32 v107, v95
	v_exp_f32_e32 v95, v119
	v_add_f32_e32 v108, 1.0, v108
	v_rcp_f32_e32 v110, v108
	v_exp_f32_e32 v108, v118
	v_add_f32_e32 v95, 1.0, v95
	v_rcp_f32_e32 v111, v95
	v_exp_f32_e32 v95, v117
	v_add_f32_e32 v108, 1.0, v108
	v_rcp_f32_e32 v124, v108
	v_exp_f32_e32 v108, v116
	v_add_f32_e32 v95, 1.0, v95
	v_rcp_f32_e32 v125, v95
	v_pk_fma_f32 v[110:111], v[110:111], s[26:27], 0.5 op_sel_hi:[1,0,0]
	v_add_f32_e32 v95, 1.0, v108
	v_rcp_f32_e32 v126, v95
	v_add_f32_e32 v95, 1.0, v109
	v_rcp_f32_e32 v127, v95
	s_cmp_eq_u32 s80, 2
	v_pk_fma_f32 v[128:129], v[106:107], s[26:27], 0.5 op_sel_hi:[1,0,0]
	v_cvt_u32_f32_e32 v109, v110
	v_cvt_u32_f32_e32 v123, v111
	s_cselect_b32 s4, 0x80, 0
	v_cvt_u32_f32_e32 v95, v129
	v_cvt_u32_f32_e32 v107, v128
	v_pk_fma_f32 v[110:111], v[124:125], s[26:27], 0.5 op_sel_hi:[1,0,0]
	s_or_b32 s4, s4, s79
	v_cvt_u32_f32_sdwa v124, v110 dst_sel:WORD_1 dst_unused:UNUSED_PAD src0_sel:DWORD
	v_cvt_u32_f32_sdwa v125, v111 dst_sel:WORD_1 dst_unused:UNUSED_PAD src0_sel:DWORD
	s_add_i32 s4, s4, s9
	s_lshr_b32 s98, s4, 7
	s_and_b32 s98, s98, 14
	s_bfe_u32 s99, s4, 0x10006
	s_or_b32 s98, s98, s99
	v_sub_u32_e32 v230, s98, v1
	s_lshr_b32 s98, s4, 11
	s_lshl_b32 s98, s98, 11
	s_and_b32 s99, s4, 128
	s_lshl_b32 s99, s99, 3
	s_add_i32 s98, s98, s99
	s_and_b32 s99, s4, 32
	s_lshl_b32 s99, s99, 4
	s_add_i32 s98, s98, s99
	v_pk_fma_f32 v[110:111], v[126:127], s[26:27], 0.5 op_sel_hi:[1,0,0]
	v_lshl_add_u32 v108, v114, 7, s98
	v_lshl_add_u32 v108, v1, 3, v108
	v_mad_i32_i24 v108, v230, s33, v108
	v_cvt_u32_f32_sdwa v110, v110 dst_sel:BYTE_3 dst_unused:UNUSED_PAD src0_sel:DWORD
	v_cvt_u32_f32_sdwa v111, v111 dst_sel:BYTE_3 dst_unused:UNUSED_PAD src0_sel:DWORD
	v_lshlrev_b32_e32 v123, 8, v123
	v_lshlrev_b32_e32 v109, 8, v109
	v_or_b32_e32 v95, v123, v95
	v_or_b32_e32 v107, v109, v107
	v_ashrrev_i32_e32 v109, 31, v108
	v_or_b32_e32 v95, v95, v125
	v_or_b32_e32 v107, v107, v124
	v_lshl_add_u64 v[124:125], v[98:99], 0, v[108:109]
	v_add_co_u32_e32 v124, vcc, s12, v124
	v_or_b32_e32 v111, v95, v111
	v_or_b32_e32 v110, v107, v110
	v_addc_co_u32_e32 v125, vcc, 0, v125, vcc
	global_store_dwordx2 v[124:125], v[110:111], off nt
	v_pk_mul_f32 v[124:125], v[54:55], v[92:93] op_sel_hi:[1,0]
	v_pk_mul_f32 v[126:127], v[50:51], v[92:93] op_sel_hi:[1,0]
	v_mul_f32_e32 v95, 0xbfb8aa3b, v124
	v_exp_f32_e32 v95, v95
	v_mul_f32_e32 v107, 0xbfb8aa3b, v126
	v_exp_f32_e32 v107, v107
	v_mul_f32_e32 v123, 0xbfb8aa3b, v127
	v_add_f32_e32 v95, 1.0, v95
	v_rcp_f32_e32 v124, v95
	v_add_f32_e32 v95, 1.0, v107
	v_mul_f32_e32 v107, 0xbfb8aa3b, v125
	v_exp_f32_e32 v107, v107
	v_pk_mul_f32 v[110:111], v[56:57], v[92:93] op_sel_hi:[1,0]
	v_exp_f32_e32 v123, v123
	v_rcp_f32_e32 v125, v95
	v_add_f32_e32 v95, 1.0, v107
	v_mul_f32_e32 v107, 0xbfb8aa3b, v110
	v_pk_mul_f32 v[128:129], v[52:53], v[92:93] op_sel_hi:[1,0]
	v_exp_f32_e32 v107, v107
	v_mul_f32_e32 v110, 0xbfb8aa3b, v128
	v_rcp_f32_e32 v126, v95
	v_add_f32_e32 v95, 1.0, v123
	v_exp_f32_e32 v123, v110
	v_rcp_f32_e32 v127, v95
	v_add_f32_e32 v95, 1.0, v107
	v_mul_f32_e32 v107, 0xbfb8aa3b, v111
	v_exp_f32_e32 v107, v107
	v_mul_f32_e32 v111, 0xbfb8aa3b, v129
	v_rcp_f32_e32 v110, v95
	v_add_f32_e32 v95, 1.0, v123
	v_exp_f32_e32 v123, v111
	v_rcp_f32_e32 v111, v95
	v_add_f32_e32 v95, 1.0, v107
	v_rcp_f32_e32 v128, v95
	v_add_f32_e32 v95, 1.0, v123
	v_rcp_f32_e32 v129, v95
	v_pk_fma_f32 v[124:125], v[124:125], s[26:27], 0.5 op_sel_hi:[1,0,0]
	v_pk_fma_f32 v[110:111], v[110:111], s[26:27], 0.5 op_sel_hi:[1,0,0]
	v_cvt_u32_f32_e32 v95, v125
	v_cvt_u32_f32_e32 v107, v124
	v_pk_fma_f32 v[124:125], v[126:127], s[26:27], 0.5 op_sel_hi:[1,0,0]
	v_cvt_u32_f32_sdwa v126, v111 dst_sel:WORD_1 dst_unused:UNUSED_PAD src0_sel:DWORD
	v_cvt_u32_f32_e32 v123, v124
	v_cvt_u32_f32_e32 v124, v125
	v_cvt_u32_f32_sdwa v125, v110 dst_sel:WORD_1 dst_unused:UNUSED_PAD src0_sel:DWORD
	v_pk_fma_f32 v[110:111], v[128:129], s[26:27], 0.5 op_sel_hi:[1,0,0]
	v_lshlrev_b32_e32 v123, 8, v123
	v_cvt_u32_f32_sdwa v110, v110 dst_sel:BYTE_3 dst_unused:UNUSED_PAD src0_sel:DWORD
	v_cvt_u32_f32_sdwa v111, v111 dst_sel:BYTE_3 dst_unused:UNUSED_PAD src0_sel:DWORD
	v_lshlrev_b32_e32 v124, 8, v124
	v_or_b32_e32 v95, v124, v95
	v_or_b32_e32 v107, v123, v107
	v_or_b32_e32 v95, v95, v126
	v_or_b32_e32 v107, v107, v125
	v_or_b32_e32 v125, v95, v111
	v_or_b32_e32 v124, v107, v110
	v_mov_b64_e32 v[110:111], s[68:69]
	v_mad_i64_i32 v[126:127], s[4:5], v113, s33, v[110:111]
	v_lshl_add_u64 v[126:127], v[126:127], 0, v[108:109]
; __device__ __forceinline__ float sigmoid_f(float x) { return __builtin_amdgcn_rcpf(1.0f + __builtin_amdgcn_exp2f(-1.4426950409f * x)); }
;     __device__ __forceinline__ void body_gate(f32x4 (&acc)[2][2][4][2], const Unit& u, int wr, int wc, int fr, int fq, int gbase, const float (&rsv)[2][4]) const {
;         EPI_ROWS_BEGIN
;             const float rs = rsv[ai][m];
; #pragma unroll
;             for (int bj = 0; bj < 2; ++bj) { if (u.half != 0 && bj == 1) continue;
;                 const int gcol = gbase + (bj + (u.half == 2 ? 1 : 0)) * 128 + wc * 32 + 8 * fq;
;                 f32x4 v0 = acc[ai][bj][m][0] * rs, v1 = acc[ai][bj][m][1] * rs;
; #pragma unroll
;                 for (int j = 0; j < 4; ++j) { v0[j] = sigmoid_f(v0[j]); v1[j] = sigmoid_f(v1[j]); }
;                 u32x2 w; w.x = pk_unorm8(v0); w.y = pk_unorm8(v1);
;                 *(u32x2*)((unsigned char*)P + (size_t)row * ROWB + GATE_B0 + gcol) = w;
;             }
;         EPI_END
;     }
	v_add_co_u32_e32 v126, vcc, s12, v126
	v_pk_mul_f32 v[128:129], v[42:43], v[90:91] op_sel_hi:[1,0]
	s_nop 0
	v_addc_co_u32_e32 v127, vcc, 0, v127, vcc
	global_store_dwordx2 v[126:127], v[124:125], off nt
	v_pk_mul_f32 v[126:127], v[46:47], v[90:91] op_sel_hi:[1,0]
	v_mul_f32_e32 v107, 0xbfb8aa3b, v128
	v_mul_f32_e32 v95, 0xbfb8aa3b, v126
	v_exp_f32_e32 v95, v95
	v_exp_f32_e32 v107, v107
	v_mul_f32_e32 v123, 0xbfb8aa3b, v129
	v_exp_f32_e32 v123, v123
	v_add_f32_e32 v95, 1.0, v95
	v_rcp_f32_e32 v126, v95
	v_add_f32_e32 v95, 1.0, v107
	v_mul_f32_e32 v107, 0xbfb8aa3b, v127
	v_exp_f32_e32 v107, v107
	v_pk_mul_f32 v[124:125], v[48:49], v[90:91] op_sel_hi:[1,0]
	v_pk_mul_f32 v[130:131], v[44:45], v[90:91] op_sel_hi:[1,0]
	v_rcp_f32_e32 v127, v95
	v_add_f32_e32 v95, 1.0, v107
	v_mul_f32_e32 v107, 0xbfb8aa3b, v124
	v_rcp_f32_e32 v128, v95
	v_add_f32_e32 v95, 1.0, v123
	v_exp_f32_e32 v107, v107
	v_mul_f32_e32 v123, 0xbfb8aa3b, v130
	v_exp_f32_e32 v123, v123
	v_rcp_f32_e32 v129, v95
	v_add_f32_e32 v95, 1.0, v107
	v_mul_f32_e32 v107, 0xbfb8aa3b, v125
	v_rcp_f32_e32 v124, v95
	v_add_f32_e32 v95, 1.0, v123
	v_exp_f32_e32 v107, v107
	v_mul_f32_e32 v123, 0xbfb8aa3b, v131
	v_exp_f32_e32 v123, v123
	v_rcp_f32_e32 v125, v95
	v_add_f32_e32 v95, 1.0, v107
	v_rcp_f32_e32 v130, v95
	v_add_f32_e32 v95, 1.0, v123
	v_pk_fma_f32 v[126:127], v[126:127], s[26:27], 0.5 op_sel_hi:[1,0,0]
	v_rcp_f32_e32 v131, v95
	v_cvt_u32_f32_e32 v95, v127
	v_cvt_u32_f32_e32 v107, v126
	v_pk_fma_f32 v[126:127], v[128:129], s[26:27], 0.5 op_sel_hi:[1,0,0]
	v_pk_fma_f32 v[124:125], v[124:125], s[26:27], 0.5 op_sel_hi:[1,0,0]
	v_cvt_u32_f32_e32 v123, v126
	v_cvt_u32_f32_e32 v126, v127
	v_cvt_u32_f32_sdwa v127, v124 dst_sel:WORD_1 dst_unused:UNUSED_PAD src0_sel:DWORD
	v_cvt_u32_f32_sdwa v128, v125 dst_sel:WORD_1 dst_unused:UNUSED_PAD src0_sel:DWORD
	v_pk_fma_f32 v[124:125], v[130:131], s[26:27], 0.5 op_sel_hi:[1,0,0]
	v_lshlrev_b32_e32 v123, 8, v123
	v_cvt_u32_f32_sdwa v124, v124 dst_sel:BYTE_3 dst_unused:UNUSED_PAD src0_sel:DWORD
	v_cvt_u32_f32_sdwa v125, v125 dst_sel:BYTE_3 dst_unused:UNUSED_PAD src0_sel:DWORD
	v_lshlrev_b32_e32 v126, 8, v126
	v_or_b32_e32 v107, v123, v107
	v_or_b32_e32 v95, v126, v95
	v_or_b32_e32 v107, v107, v127
	v_mad_i64_i32 v[126:127], s[4:5], v112, s33, v[110:111]
	v_lshl_add_u64 v[126:127], v[126:127], 0, v[108:109]
	v_or_b32_e32 v95, v95, v128
	v_add_co_u32_e32 v126, vcc, s12, v126
	v_or_b32_e32 v125, v95, v125
	v_or_b32_e32 v124, v107, v124
	v_addc_co_u32_e32 v127, vcc, 0, v127, vcc
	global_store_dwordx2 v[126:127], v[124:125], off nt
	v_pk_mul_f32 v[126:127], v[38:39], v[86:87] op_sel_hi:[1,0]
	v_pk_mul_f32 v[128:129], v[34:35], v[86:87] op_sel_hi:[1,0]
	v_mul_f32_e32 v95, 0xbfb8aa3b, v126
	v_exp_f32_e32 v95, v95
	v_mul_f32_e32 v107, 0xbfb8aa3b, v128
	v_exp_f32_e32 v107, v107
	v_mul_f32_e32 v123, 0xbfb8aa3b, v129
	v_add_f32_e32 v95, 1.0, v95
	v_rcp_f32_e32 v126, v95
	v_add_f32_e32 v95, 1.0, v107
	v_mul_f32_e32 v107, 0xbfb8aa3b, v127
	v_exp_f32_e32 v107, v107
	v_exp_f32_e32 v123, v123
	v_pk_mul_f32 v[124:125], v[40:41], v[86:87] op_sel_hi:[1,0]
	v_pk_mul_f32 v[130:131], v[36:37], v[86:87] op_sel_hi:[1,0]
	v_rcp_f32_e32 v127, v95
	v_add_f32_e32 v95, 1.0, v107
	v_mul_f32_e32 v107, 0xbfb8aa3b, v124
	v_rcp_f32_e32 v128, v95
	v_add_f32_e32 v95, 1.0, v123
	v_exp_f32_e32 v107, v107
	v_mul_f32_e32 v123, 0xbfb8aa3b, v130
	v_exp_f32_e32 v123, v123
	v_rcp_f32_e32 v129, v95
	v_add_f32_e32 v95, 1.0, v107
	v_mul_f32_e32 v107, 0xbfb8aa3b, v125
	v_rcp_f32_e32 v124, v95
	v_add_f32_e32 v95, 1.0, v123
	v_exp_f32_e32 v107, v107
	v_mul_f32_e32 v123, 0xbfb8aa3b, v131
	v_exp_f32_e32 v123, v123
	v_rcp_f32_e32 v125, v95
	v_add_f32_e32 v95, 1.0, v107
	v_rcp_f32_e32 v130, v95
	v_add_f32_e32 v95, 1.0, v123
	v_pk_fma_f32 v[126:127], v[126:127], s[26:27], 0.5 op_sel_hi:[1,0,0]
	v_rcp_f32_e32 v131, v95
	v_cvt_u32_f32_e32 v95, v127
	v_cvt_u32_f32_e32 v107, v126
	v_pk_fma_f32 v[126:127], v[128:129], s[26:27], 0.5 op_sel_hi:[1,0,0]
	v_pk_fma_f32 v[124:125], v[124:125], s[26:27], 0.5 op_sel_hi:[1,0,0]
	v_cvt_u32_f32_e32 v123, v126
	v_cvt_u32_f32_e32 v126, v127
	v_cvt_u32_f32_sdwa v127, v124 dst_sel:WORD_1 dst_unused:UNUSED_PAD src0_sel:DWORD
	v_cvt_u32_f32_sdwa v128, v125 dst_sel:WORD_1 dst_unused:UNUSED_PAD src0_sel:DWORD
	v_pk_fma_f32 v[124:125], v[130:131], s[26:27], 0.5 op_sel_hi:[1,0,0]
	v_lshlrev_b32_e32 v123, 8, v123
	v_cvt_u32_f32_sdwa v124, v124 dst_sel:BYTE_3 dst_unused:UNUSED_PAD src0_sel:DWORD
	v_cvt_u32_f32_sdwa v125, v125 dst_sel:BYTE_3 dst_unused:UNUSED_PAD src0_sel:DWORD
	v_lshlrev_b32_e32 v126, 8, v126
	v_or_b32_e32 v107, v123, v107
	v_or_b32_e32 v95, v126, v95
	v_or_b32_e32 v107, v107, v127
	v_mad_i64_i32 v[126:127], s[4:5], v93, s33, v[110:111]
	v_lshl_add_u64 v[126:127], v[126:127], 0, v[108:109]
	v_or_b32_e32 v95, v95, v128
	v_add_co_u32_e32 v126, vcc, s12, v126
	v_or_b32_e32 v125, v95, v125
	v_or_b32_e32 v124, v107, v124
	v_addc_co_u32_e32 v127, vcc, 0, v127, vcc
	global_store_dwordx2 v[126:127], v[124:125], off nt
	v_pk_mul_f32 v[126:127], v[30:31], v[84:85] op_sel_hi:[1,0]
	v_pk_mul_f32 v[128:129], v[26:27], v[84:85] op_sel_hi:[1,0]
	v_mul_f32_e32 v95, 0xbfb8aa3b, v126
	v_exp_f32_e32 v95, v95
	v_mul_f32_e32 v107, 0xbfb8aa3b, v128
	v_exp_f32_e32 v107, v107
	v_mul_f32_e32 v123, 0xbfb8aa3b, v129
	v_add_f32_e32 v95, 1.0, v95
	v_rcp_f32_e32 v126, v95
	v_add_f32_e32 v95, 1.0, v107
	v_mul_f32_e32 v107, 0xbfb8aa3b, v127
	v_exp_f32_e32 v107, v107
	v_exp_f32_e32 v123, v123
	v_pk_mul_f32 v[124:125], v[32:33], v[84:85] op_sel_hi:[1,0]
	v_pk_mul_f32 v[130:131], v[28:29], v[84:85] op_sel_hi:[1,0]
	v_rcp_f32_e32 v127, v95
	v_add_f32_e32 v95, 1.0, v107
	v_mul_f32_e32 v107, 0xbfb8aa3b, v124
; __device__ __forceinline__ float sigmoid_f(float x) { return __builtin_amdgcn_rcpf(1.0f + __builtin_amdgcn_exp2f(-1.4426950409f * x)); }
;     __device__ __forceinline__ void body_gate(f32x4 (&acc)[2][2][4][2], const Unit& u, int wr, int wc, int fr, int fq, int gbase, const float (&rsv)[2][4]) const {
;         EPI_ROWS_BEGIN
;             const float rs = rsv[ai][m];
; #pragma unroll
;             for (int bj = 0; bj < 2; ++bj) { if (u.half != 0 && bj == 1) continue;
;                 const int gcol = gbase + (bj + (u.half == 2 ? 1 : 0)) * 128 + wc * 32 + 8 * fq;
;                 f32x4 v0 = acc[ai][bj][m][0] * rs, v1 = acc[ai][bj][m][1] * rs;
; #pragma unroll
;                 for (int j = 0; j < 4; ++j) { v0[j] = sigmoid_f(v0[j]); v1[j] = sigmoid_f(v1[j]); }
;                 u32x2 w; w.x = pk_unorm8(v0); w.y = pk_unorm8(v1);
;                 *(u32x2*)((unsigned char*)P + (size_t)row * ROWB + GATE_B0 + gcol) = w;
;             }
;         EPI_END
;     }
	v_rcp_f32_e32 v128, v95
	v_add_f32_e32 v95, 1.0, v123
	v_exp_f32_e32 v107, v107
	v_mul_f32_e32 v123, 0xbfb8aa3b, v130
	v_exp_f32_e32 v123, v123
	v_rcp_f32_e32 v129, v95
	v_add_f32_e32 v95, 1.0, v107
	v_mul_f32_e32 v107, 0xbfb8aa3b, v125
	v_rcp_f32_e32 v124, v95
	v_add_f32_e32 v95, 1.0, v123
	v_exp_f32_e32 v107, v107
	v_mul_f32_e32 v123, 0xbfb8aa3b, v131
	v_exp_f32_e32 v123, v123
	v_rcp_f32_e32 v125, v95
	v_add_f32_e32 v95, 1.0, v107
	v_rcp_f32_e32 v130, v95
	v_add_f32_e32 v95, 1.0, v123
	v_pk_fma_f32 v[126:127], v[126:127], s[26:27], 0.5 op_sel_hi:[1,0,0]
	v_rcp_f32_e32 v131, v95
	v_cvt_u32_f32_e32 v95, v127
	v_cvt_u32_f32_e32 v107, v126
	v_pk_fma_f32 v[126:127], v[128:129], s[26:27], 0.5 op_sel_hi:[1,0,0]
	v_pk_fma_f32 v[124:125], v[124:125], s[26:27], 0.5 op_sel_hi:[1,0,0]
	v_cvt_u32_f32_e32 v123, v126
	v_cvt_u32_f32_e32 v126, v127
	v_cvt_u32_f32_sdwa v127, v124 dst_sel:WORD_1 dst_unused:UNUSED_PAD src0_sel:DWORD
	v_cvt_u32_f32_sdwa v128, v125 dst_sel:WORD_1 dst_unused:UNUSED_PAD src0_sel:DWORD
	v_pk_fma_f32 v[124:125], v[130:131], s[26:27], 0.5 op_sel_hi:[1,0,0]
	v_lshlrev_b32_e32 v123, 8, v123
	v_cvt_u32_f32_sdwa v124, v124 dst_sel:BYTE_3 dst_unused:UNUSED_PAD src0_sel:DWORD
	v_cvt_u32_f32_sdwa v125, v125 dst_sel:BYTE_3 dst_unused:UNUSED_PAD src0_sel:DWORD
	v_lshlrev_b32_e32 v126, 8, v126
	v_or_b32_e32 v107, v123, v107
	v_or_b32_e32 v95, v126, v95
	v_or_b32_e32 v107, v107, v127
	v_mad_i64_i32 v[126:127], s[4:5], v91, s33, v[110:111]
	v_lshl_add_u64 v[126:127], v[126:127], 0, v[108:109]
	v_or_b32_e32 v95, v95, v128
	v_add_co_u32_e32 v126, vcc, s12, v126
	v_or_b32_e32 v125, v95, v125
	v_or_b32_e32 v124, v107, v124
	v_addc_co_u32_e32 v127, vcc, 0, v127, vcc
	global_store_dwordx2 v[126:127], v[124:125], off nt
	v_pk_mul_f32 v[126:127], v[22:23], v[82:83] op_sel_hi:[1,0]
	v_pk_mul_f32 v[128:129], v[18:19], v[82:83] op_sel_hi:[1,0]
	v_mul_f32_e32 v95, 0xbfb8aa3b, v126
	v_exp_f32_e32 v95, v95
	v_mul_f32_e32 v107, 0xbfb8aa3b, v128
	v_exp_f32_e32 v107, v107
	v_mul_f32_e32 v123, 0xbfb8aa3b, v129
	v_add_f32_e32 v95, 1.0, v95
	v_rcp_f32_e32 v126, v95
	v_add_f32_e32 v95, 1.0, v107
	v_mul_f32_e32 v107, 0xbfb8aa3b, v127
	v_exp_f32_e32 v107, v107
	v_exp_f32_e32 v123, v123
	v_pk_mul_f32 v[124:125], v[24:25], v[82:83] op_sel_hi:[1,0]
	v_pk_mul_f32 v[130:131], v[20:21], v[82:83] op_sel_hi:[1,0]
	v_rcp_f32_e32 v127, v95
	v_add_f32_e32 v95, 1.0, v107
	v_mul_f32_e32 v107, 0xbfb8aa3b, v124
	v_rcp_f32_e32 v128, v95
	v_add_f32_e32 v95, 1.0, v123
	v_exp_f32_e32 v107, v107
	v_mul_f32_e32 v123, 0xbfb8aa3b, v130
	v_exp_f32_e32 v123, v123
	v_rcp_f32_e32 v129, v95
	v_add_f32_e32 v95, 1.0, v107
	v_mul_f32_e32 v107, 0xbfb8aa3b, v125
	v_rcp_f32_e32 v124, v95
	v_add_f32_e32 v95, 1.0, v123
	v_exp_f32_e32 v107, v107
	v_mul_f32_e32 v123, 0xbfb8aa3b, v131
	v_exp_f32_e32 v123, v123
	v_rcp_f32_e32 v125, v95
	v_add_f32_e32 v95, 1.0, v107
	v_rcp_f32_e32 v130, v95
	v_add_f32_e32 v95, 1.0, v123
	v_pk_fma_f32 v[126:127], v[126:127], s[26:27], 0.5 op_sel_hi:[1,0,0]
	v_rcp_f32_e32 v131, v95
	v_cvt_u32_f32_e32 v95, v127
	v_cvt_u32_f32_e32 v107, v126
	v_pk_fma_f32 v[126:127], v[128:129], s[26:27], 0.5 op_sel_hi:[1,0,0]
	v_pk_fma_f32 v[124:125], v[124:125], s[26:27], 0.5 op_sel_hi:[1,0,0]
	v_cvt_u32_f32_e32 v123, v126
	v_cvt_u32_f32_e32 v126, v127
	v_cvt_u32_f32_sdwa v127, v124 dst_sel:WORD_1 dst_unused:UNUSED_PAD src0_sel:DWORD
	v_cvt_u32_f32_sdwa v128, v125 dst_sel:WORD_1 dst_unused:UNUSED_PAD src0_sel:DWORD
	v_pk_fma_f32 v[124:125], v[130:131], s[26:27], 0.5 op_sel_hi:[1,0,0]
	v_lshlrev_b32_e32 v123, 8, v123
	v_cvt_u32_f32_sdwa v124, v124 dst_sel:BYTE_3 dst_unused:UNUSED_PAD src0_sel:DWORD
	v_cvt_u32_f32_sdwa v125, v125 dst_sel:BYTE_3 dst_unused:UNUSED_PAD src0_sel:DWORD
	v_lshlrev_b32_e32 v126, 8, v126
	v_or_b32_e32 v107, v123, v107
	v_or_b32_e32 v95, v126, v95
	v_or_b32_e32 v107, v107, v127
	v_mad_i64_i32 v[126:127], s[4:5], v89, s33, v[110:111]
	v_lshl_add_u64 v[126:127], v[126:127], 0, v[108:109]
	v_or_b32_e32 v95, v95, v128
	v_add_co_u32_e32 v126, vcc, s12, v126
	v_or_b32_e32 v125, v95, v125
	v_or_b32_e32 v124, v107, v124
	v_addc_co_u32_e32 v127, vcc, 0, v127, vcc
	global_store_dwordx2 v[126:127], v[124:125], off nt
	v_pk_mul_f32 v[126:127], v[14:15], v[80:81] op_sel_hi:[1,0]
	v_pk_mul_f32 v[128:129], v[10:11], v[80:81] op_sel_hi:[1,0]
	v_mul_f32_e32 v95, 0xbfb8aa3b, v126
	v_exp_f32_e32 v95, v95
	v_mul_f32_e32 v107, 0xbfb8aa3b, v128
	v_exp_f32_e32 v107, v107
	v_mul_f32_e32 v123, 0xbfb8aa3b, v129
	v_add_f32_e32 v95, 1.0, v95
	v_rcp_f32_e32 v126, v95
; __device__ __forceinline__ float sigmoid_f(float x) { return __builtin_amdgcn_rcpf(1.0f + __builtin_amdgcn_exp2f(-1.4426950409f * x)); }
;     __device__ __forceinline__ void body_gate(f32x4 (&acc)[2][2][4][2], const Unit& u, int wr, int wc, int fr, int fq, int gbase, const float (&rsv)[2][4]) const {
;         EPI_ROWS_BEGIN
;             const float rs = rsv[ai][m];
; #pragma unroll
;             for (int bj = 0; bj < 2; ++bj) { if (u.half != 0 && bj == 1) continue;
;                 const int gcol = gbase + (bj + (u.half == 2 ? 1 : 0)) * 128 + wc * 32 + 8 * fq;
;                 f32x4 v0 = acc[ai][bj][m][0] * rs, v1 = acc[ai][bj][m][1] * rs;
; #pragma unroll
;                 for (int j = 0; j < 4; ++j) { v0[j] = sigmoid_f(v0[j]); v1[j] = sigmoid_f(v1[j]); }
;                 u32x2 w; w.x = pk_unorm8(v0); w.y = pk_unorm8(v1);
;                 *(u32x2*)((unsigned char*)P + (size_t)row * ROWB + GATE_B0 + gcol) = w;
;             }
;         EPI_END
;     }
	v_add_f32_e32 v95, 1.0, v107
	v_mul_f32_e32 v107, 0xbfb8aa3b, v127
	v_exp_f32_e32 v107, v107
	v_exp_f32_e32 v123, v123
	v_pk_mul_f32 v[124:125], v[16:17], v[80:81] op_sel_hi:[1,0]
	v_pk_mul_f32 v[130:131], v[12:13], v[80:81] op_sel_hi:[1,0]
	v_rcp_f32_e32 v127, v95
	v_add_f32_e32 v95, 1.0, v107
	v_mul_f32_e32 v107, 0xbfb8aa3b, v124
	v_rcp_f32_e32 v128, v95
	v_add_f32_e32 v95, 1.0, v123
	v_exp_f32_e32 v107, v107
	v_mul_f32_e32 v123, 0xbfb8aa3b, v130
	v_exp_f32_e32 v123, v123
	v_rcp_f32_e32 v129, v95
	v_add_f32_e32 v95, 1.0, v107
	v_mul_f32_e32 v107, 0xbfb8aa3b, v125
	v_rcp_f32_e32 v124, v95
	v_add_f32_e32 v95, 1.0, v123
	v_exp_f32_e32 v107, v107
	v_mul_f32_e32 v123, 0xbfb8aa3b, v131
	v_exp_f32_e32 v123, v123
	v_rcp_f32_e32 v125, v95
	v_add_f32_e32 v95, 1.0, v107
	v_rcp_f32_e32 v130, v95
	v_add_f32_e32 v95, 1.0, v123
	v_pk_fma_f32 v[126:127], v[126:127], s[26:27], 0.5 op_sel_hi:[1,0,0]
	v_rcp_f32_e32 v131, v95
	v_cvt_u32_f32_e32 v95, v127
	v_cvt_u32_f32_e32 v107, v126
	v_pk_fma_f32 v[126:127], v[128:129], s[26:27], 0.5 op_sel_hi:[1,0,0]
	v_pk_fma_f32 v[124:125], v[124:125], s[26:27], 0.5 op_sel_hi:[1,0,0]
	v_cvt_u32_f32_e32 v123, v126
	v_cvt_u32_f32_e32 v126, v127
	v_cvt_u32_f32_sdwa v127, v124 dst_sel:WORD_1 dst_unused:UNUSED_PAD src0_sel:DWORD
	v_cvt_u32_f32_sdwa v128, v125 dst_sel:WORD_1 dst_unused:UNUSED_PAD src0_sel:DWORD
	v_pk_fma_f32 v[124:125], v[130:131], s[26:27], 0.5 op_sel_hi:[1,0,0]
	v_lshlrev_b32_e32 v123, 8, v123
	v_cvt_u32_f32_sdwa v124, v124 dst_sel:BYTE_3 dst_unused:UNUSED_PAD src0_sel:DWORD
	v_cvt_u32_f32_sdwa v125, v125 dst_sel:BYTE_3 dst_unused:UNUSED_PAD src0_sel:DWORD
	v_lshlrev_b32_e32 v126, 8, v126
	v_or_b32_e32 v107, v123, v107
	v_or_b32_e32 v95, v126, v95
	v_or_b32_e32 v107, v107, v127
	v_mad_i64_i32 v[126:127], s[4:5], v87, s33, v[110:111]
	v_lshl_add_u64 v[126:127], v[126:127], 0, v[108:109]
	v_or_b32_e32 v95, v95, v128
	v_add_co_u32_e32 v126, vcc, s12, v126
	v_or_b32_e32 v125, v95, v125
	v_or_b32_e32 v124, v107, v124
	v_addc_co_u32_e32 v127, vcc, 0, v127, vcc
	global_store_dwordx2 v[126:127], v[124:125], off nt
	v_pk_mul_f32 v[126:127], v[6:7], v[78:79] op_sel_hi:[1,0]
	v_pk_mul_f32 v[128:129], v[2:3], v[78:79] op_sel_hi:[1,0]
	v_mul_f32_e32 v95, 0xbfb8aa3b, v126
	v_exp_f32_e32 v95, v95
	v_mul_f32_e32 v107, 0xbfb8aa3b, v128
	v_exp_f32_e32 v107, v107
	v_mul_f32_e32 v123, 0xbfb8aa3b, v129
	v_add_f32_e32 v95, 1.0, v95
	v_rcp_f32_e32 v126, v95
	v_add_f32_e32 v95, 1.0, v107
	v_mul_f32_e32 v107, 0xbfb8aa3b, v127
	v_exp_f32_e32 v107, v107
	v_exp_f32_e32 v123, v123
	v_pk_mul_f32 v[124:125], v[8:9], v[78:79] op_sel_hi:[1,0]
	v_pk_mul_f32 v[130:131], v[4:5], v[78:79] op_sel_hi:[1,0]
	v_rcp_f32_e32 v127, v95
	v_add_f32_e32 v95, 1.0, v107
	v_mul_f32_e32 v107, 0xbfb8aa3b, v124
	v_rcp_f32_e32 v128, v95
	v_add_f32_e32 v95, 1.0, v123
	v_exp_f32_e32 v107, v107
	v_mul_f32_e32 v123, 0xbfb8aa3b, v130
	v_exp_f32_e32 v123, v123
	v_rcp_f32_e32 v129, v95
	v_add_f32_e32 v95, 1.0, v107
	v_mul_f32_e32 v107, 0xbfb8aa3b, v125
	v_rcp_f32_e32 v124, v95
	v_add_f32_e32 v95, 1.0, v123
	v_exp_f32_e32 v107, v107
	v_mul_f32_e32 v123, 0xbfb8aa3b, v131
	v_exp_f32_e32 v123, v123
	v_rcp_f32_e32 v125, v95
	v_add_f32_e32 v95, 1.0, v107
	v_rcp_f32_e32 v130, v95
	v_add_f32_e32 v95, 1.0, v123
	v_rcp_f32_e32 v131, v95
	v_pk_fma_f32 v[126:127], v[126:127], s[26:27], 0.5 op_sel_hi:[1,0,0]
	v_pk_fma_f32 v[124:125], v[124:125], s[26:27], 0.5 op_sel_hi:[1,0,0]
	v_cvt_u32_f32_e32 v95, v127
	v_cvt_u32_f32_e32 v107, v126
	v_pk_fma_f32 v[126:127], v[128:129], s[26:27], 0.5 op_sel_hi:[1,0,0]
	v_cvt_u32_f32_sdwa v128, v125 dst_sel:WORD_1 dst_unused:UNUSED_PAD src0_sel:DWORD
	v_cvt_u32_f32_e32 v123, v126
	v_cvt_u32_f32_e32 v126, v127
	v_cvt_u32_f32_sdwa v127, v124 dst_sel:WORD_1 dst_unused:UNUSED_PAD src0_sel:DWORD
	v_pk_fma_f32 v[124:125], v[130:131], s[26:27], 0.5 op_sel_hi:[1,0,0]
	v_lshlrev_b32_e32 v123, 8, v123
	v_cvt_u32_f32_sdwa v124, v124 dst_sel:BYTE_3 dst_unused:UNUSED_PAD src0_sel:DWORD
	v_cvt_u32_f32_sdwa v125, v125 dst_sel:BYTE_3 dst_unused:UNUSED_PAD src0_sel:DWORD
	v_lshlrev_b32_e32 v126, 8, v126
	v_mad_i64_i32 v[110:111], s[4:5], v85, s33, v[110:111]
	v_or_b32_e32 v95, v126, v95
	v_or_b32_e32 v107, v123, v107
	v_lshl_add_u64 v[108:109], v[110:111], 0, v[108:109]
	v_or_b32_e32 v95, v95, v128
	v_or_b32_e32 v107, v107, v127
	v_add_co_u32_e32 v108, vcc, 0x3000, v108
	v_or_b32_e32 v125, v95, v125
	v_or_b32_e32 v124, v107, v124
	v_addc_co_u32_e32 v109, vcc, 0, v109, vcc
	global_store_dwordx2 v[108:109], v[124:125], off nt
	s_mov_b64 s[4:5], 0
